# forget-gate logits pass: 32 row loads in flight per trip instead of hipcc's 4-6
# speedup vs baseline: 1.0066x; 1.0066x over previous
.LBB0_462:
	global_load_dwordx4 v[84:87], v[16:17], off offset:-480
	global_load_dwordx4 v[88:91], v[16:17], off offset:-448
	global_load_dwordx4 v[92:95], v[16:17], off offset:-416
	global_load_dwordx4 v[96:99], v[16:17], off offset:-384
	global_load_dwordx4 v[100:103], v[16:17], off offset:-352
	global_load_dwordx4 v[104:107], v[16:17], off offset:-320
	global_load_dwordx4 v[108:111], v[16:17], off offset:-288
	global_load_dwordx4 v[112:115], v[16:17], off offset:-256
	global_load_dwordx4 v[116:119], v[16:17], off offset:-224
	global_load_dwordx4 v[120:123], v[16:17], off offset:-192
	global_load_dwordx4 v[124:127], v[16:17], off offset:-160
	global_load_dwordx4 v[128:131], v[16:17], off offset:-128
	global_load_dwordx4 v[132:135], v[16:17], off offset:-96
	global_load_dwordx4 v[136:139], v[16:17], off offset:-64
	global_load_dwordx4 v[140:143], v[16:17], off offset:-32
	global_load_dwordx4 v[144:147], v[16:17], off
	global_load_dwordx4 v[148:151], v[16:17], off offset:32
	global_load_dwordx4 v[152:155], v[16:17], off offset:64
	global_load_dwordx4 v[156:159], v[16:17], off offset:96
	global_load_dwordx4 v[160:163], v[16:17], off offset:128
	global_load_dwordx4 v[164:167], v[16:17], off offset:160
	global_load_dwordx4 v[168:171], v[16:17], off offset:192
	global_load_dwordx4 v[172:175], v[16:17], off offset:224
	global_load_dwordx4 v[176:179], v[16:17], off offset:256
	global_load_dwordx4 v[180:183], v[16:17], off offset:288
	global_load_dwordx4 v[184:187], v[16:17], off offset:320
	global_load_dwordx4 v[188:191], v[16:17], off offset:352
	global_load_dwordx4 v[192:195], v[16:17], off offset:384
	global_load_dwordx4 v[196:199], v[16:17], off offset:416
	global_load_dwordx4 v[200:203], v[16:17], off offset:448
	global_load_dwordx4 v[204:207], v[16:17], off offset:480
	global_load_dwordx4 v[208:211], v[16:17], off offset:512
	s_add_i32 s10, s10, 32
	s_cmp_gt_u32 s10, 47
	v_lshl_add_u64 v[16:17], v[16:17], 0, s[42:43]
	v_lshl_add_u64 v[16:17], v[16:17], 0, s[42:43]
	ds_read_b128 v[20:23], v18
	ds_read_b128 v[32:35], v18 offset:32
	ds_read_b128 v[46:49], v18 offset:64
	s_waitcnt lgkmcnt(2)
	v_cndmask_b32_e64 v23, v23, 0, s[6:7]
	v_cndmask_b32_e64 v22, v22, 0, s[6:7]
	v_cndmask_b32_e64 v21, v21, 0, s[6:7]
	v_cndmask_b32_e64 v20, v20, 0, s[6:7]
	s_waitcnt vmcnt(31)
	s_nop 1
	v_mfma_f32_32x32x16_bf16 v[0:15], v[84:87], v[20:23], v[0:15]
	ds_read_b128 v[50:53], v18 offset:96
	s_waitcnt lgkmcnt(2)
	v_cndmask_b32_e64 v35, v35, 0, s[6:7]
	v_cndmask_b32_e64 v34, v34, 0, s[6:7]
	v_cndmask_b32_e64 v33, v33, 0, s[6:7]
	v_cndmask_b32_e64 v32, v32, 0, s[6:7]
	s_waitcnt vmcnt(30)
	s_nop 1
	v_mfma_f32_32x32x16_bf16 v[0:15], v[88:91], v[32:35], v[0:15]
	ds_read_b128 v[20:23], v18 offset:128
	s_waitcnt lgkmcnt(2)
	v_cndmask_b32_e64 v49, v49, 0, s[6:7]
	v_cndmask_b32_e64 v48, v48, 0, s[6:7]
	v_cndmask_b32_e64 v47, v47, 0, s[6:7]
	v_cndmask_b32_e64 v46, v46, 0, s[6:7]
	s_waitcnt vmcnt(29)
	s_nop 1
	v_mfma_f32_32x32x16_bf16 v[0:15], v[92:95], v[46:49], v[0:15]
	ds_read_b128 v[32:35], v18 offset:160
	s_waitcnt lgkmcnt(2)
	v_cndmask_b32_e64 v53, v53, 0, s[6:7]
	v_cndmask_b32_e64 v52, v52, 0, s[6:7]
	v_cndmask_b32_e64 v51, v51, 0, s[6:7]
	v_cndmask_b32_e64 v50, v50, 0, s[6:7]
	s_waitcnt vmcnt(28)
	s_nop 1
	v_mfma_f32_32x32x16_bf16 v[0:15], v[96:99], v[50:53], v[0:15]
	ds_read_b128 v[46:49], v18 offset:192
	s_waitcnt lgkmcnt(2)
	v_cndmask_b32_e64 v23, v23, 0, s[6:7]
	v_cndmask_b32_e64 v22, v22, 0, s[6:7]
	v_cndmask_b32_e64 v21, v21, 0, s[6:7]
	v_cndmask_b32_e64 v20, v20, 0, s[6:7]
	s_waitcnt vmcnt(27)
	s_nop 1
	v_mfma_f32_32x32x16_bf16 v[0:15], v[100:103], v[20:23], v[0:15]
	ds_read_b128 v[50:53], v18 offset:224
	s_waitcnt lgkmcnt(2)
	v_cndmask_b32_e64 v35, v35, 0, s[6:7]
	v_cndmask_b32_e64 v34, v34, 0, s[6:7]
	v_cndmask_b32_e64 v33, v33, 0, s[6:7]
	v_cndmask_b32_e64 v32, v32, 0, s[6:7]
	s_waitcnt vmcnt(26)
	s_nop 1
	v_mfma_f32_32x32x16_bf16 v[0:15], v[104:107], v[32:35], v[0:15]
	ds_read_b128 v[20:23], v18 offset:256
	s_waitcnt lgkmcnt(2)
	v_cndmask_b32_e64 v49, v49, 0, s[6:7]
	v_cndmask_b32_e64 v48, v48, 0, s[6:7]
	v_cndmask_b32_e64 v47, v47, 0, s[6:7]
	v_cndmask_b32_e64 v46, v46, 0, s[6:7]
	s_waitcnt vmcnt(25)
	s_nop 1
	v_mfma_f32_32x32x16_bf16 v[0:15], v[108:111], v[46:49], v[0:15]
	ds_read_b128 v[32:35], v18 offset:288
	s_waitcnt lgkmcnt(2)
	v_cndmask_b32_e64 v53, v53, 0, s[6:7]
	v_cndmask_b32_e64 v52, v52, 0, s[6:7]
	v_cndmask_b32_e64 v51, v51, 0, s[6:7]
	v_cndmask_b32_e64 v50, v50, 0, s[6:7]
	s_waitcnt vmcnt(24)
	s_nop 1
	v_mfma_f32_32x32x16_bf16 v[0:15], v[112:115], v[50:53], v[0:15]
	ds_read_b128 v[46:49], v18 offset:320
	s_waitcnt lgkmcnt(2)
	v_cndmask_b32_e64 v23, v23, 0, s[6:7]
	v_cndmask_b32_e64 v22, v22, 0, s[6:7]
	v_cndmask_b32_e64 v21, v21, 0, s[6:7]
	v_cndmask_b32_e64 v20, v20, 0, s[6:7]
	s_waitcnt vmcnt(23)
	s_nop 1
	v_mfma_f32_32x32x16_bf16 v[0:15], v[116:119], v[20:23], v[0:15]
	ds_read_b128 v[50:53], v18 offset:352
	s_waitcnt lgkmcnt(2)
	v_cndmask_b32_e64 v35, v35, 0, s[6:7]
	v_cndmask_b32_e64 v34, v34, 0, s[6:7]
	v_cndmask_b32_e64 v33, v33, 0, s[6:7]
	v_cndmask_b32_e64 v32, v32, 0, s[6:7]
	s_waitcnt vmcnt(22)
	s_nop 1
	v_mfma_f32_32x32x16_bf16 v[0:15], v[120:123], v[32:35], v[0:15]
	ds_read_b128 v[20:23], v18 offset:384
	s_waitcnt lgkmcnt(2)
	v_cndmask_b32_e64 v49, v49, 0, s[6:7]
	v_cndmask_b32_e64 v48, v48, 0, s[6:7]
	v_cndmask_b32_e64 v47, v47, 0, s[6:7]
	v_cndmask_b32_e64 v46, v46, 0, s[6:7]
	s_waitcnt vmcnt(21)
	s_nop 1
	v_mfma_f32_32x32x16_bf16 v[0:15], v[124:127], v[46:49], v[0:15]
	ds_read_b128 v[32:35], v18 offset:416
	s_waitcnt lgkmcnt(2)
	v_cndmask_b32_e64 v53, v53, 0, s[6:7]
	v_cndmask_b32_e64 v52, v52, 0, s[6:7]
	v_cndmask_b32_e64 v51, v51, 0, s[6:7]
	v_cndmask_b32_e64 v50, v50, 0, s[6:7]
	s_waitcnt vmcnt(20)
	s_nop 1
	v_mfma_f32_32x32x16_bf16 v[0:15], v[128:131], v[50:53], v[0:15]
	ds_read_b128 v[46:49], v18 offset:448
	s_waitcnt lgkmcnt(2)
	v_cndmask_b32_e64 v23, v23, 0, s[6:7]
	v_cndmask_b32_e64 v22, v22, 0, s[6:7]
	v_cndmask_b32_e64 v21, v21, 0, s[6:7]
	v_cndmask_b32_e64 v20, v20, 0, s[6:7]
	s_waitcnt vmcnt(19)
	s_nop 1
	v_mfma_f32_32x32x16_bf16 v[0:15], v[132:135], v[20:23], v[0:15]
	ds_read_b128 v[50:53], v18 offset:480
	s_waitcnt lgkmcnt(2)
	v_cndmask_b32_e64 v35, v35, 0, s[6:7]
	v_cndmask_b32_e64 v34, v34, 0, s[6:7]
	v_cndmask_b32_e64 v33, v33, 0, s[6:7]
	v_cndmask_b32_e64 v32, v32, 0, s[6:7]
	s_waitcnt vmcnt(18)
	s_nop 1
	v_mfma_f32_32x32x16_bf16 v[0:15], v[136:139], v[32:35], v[0:15]
	ds_read_b128 v[20:23], v18 offset:512
	s_waitcnt lgkmcnt(2)
	v_cndmask_b32_e64 v49, v49, 0, s[6:7]
	v_cndmask_b32_e64 v48, v48, 0, s[6:7]
	v_cndmask_b32_e64 v47, v47, 0, s[6:7]
	v_cndmask_b32_e64 v46, v46, 0, s[6:7]
	s_waitcnt vmcnt(17)
	s_nop 1
	v_mfma_f32_32x32x16_bf16 v[0:15], v[140:143], v[46:49], v[0:15]
	ds_read_b128 v[32:35], v18 offset:544
	s_waitcnt lgkmcnt(2)
	v_cndmask_b32_e64 v53, v53, 0, s[6:7]
	v_cndmask_b32_e64 v52, v52, 0, s[6:7]
	v_cndmask_b32_e64 v51, v51, 0, s[6:7]
	v_cndmask_b32_e64 v50, v50, 0, s[6:7]
	s_waitcnt vmcnt(16)
	s_nop 1
	v_mfma_f32_32x32x16_bf16 v[0:15], v[144:147], v[50:53], v[0:15]
	ds_read_b128 v[46:49], v18 offset:576
	s_waitcnt lgkmcnt(2)
	v_cndmask_b32_e64 v23, v23, 0, s[6:7]
	v_cndmask_b32_e64 v22, v22, 0, s[6:7]
	v_cndmask_b32_e64 v21, v21, 0, s[6:7]
	v_cndmask_b32_e64 v20, v20, 0, s[6:7]
	s_waitcnt vmcnt(15)
	s_nop 1
	v_mfma_f32_32x32x16_bf16 v[0:15], v[148:151], v[20:23], v[0:15]
	ds_read_b128 v[50:53], v18 offset:608
	s_waitcnt lgkmcnt(2)
	v_cndmask_b32_e64 v35, v35, 0, s[6:7]
	v_cndmask_b32_e64 v34, v34, 0, s[6:7]
	v_cndmask_b32_e64 v33, v33, 0, s[6:7]
	v_cndmask_b32_e64 v32, v32, 0, s[6:7]
	s_waitcnt vmcnt(14)
	s_nop 1
	v_mfma_f32_32x32x16_bf16 v[0:15], v[152:155], v[32:35], v[0:15]
	ds_read_b128 v[20:23], v18 offset:640
	s_waitcnt lgkmcnt(2)
	v_cndmask_b32_e64 v49, v49, 0, s[6:7]
	v_cndmask_b32_e64 v48, v48, 0, s[6:7]
	v_cndmask_b32_e64 v47, v47, 0, s[6:7]
	v_cndmask_b32_e64 v46, v46, 0, s[6:7]
	s_waitcnt vmcnt(13)
	s_nop 1
	v_mfma_f32_32x32x16_bf16 v[0:15], v[156:159], v[46:49], v[0:15]
	ds_read_b128 v[32:35], v18 offset:672
	s_waitcnt lgkmcnt(2)
	v_cndmask_b32_e64 v53, v53, 0, s[6:7]
	v_cndmask_b32_e64 v52, v52, 0, s[6:7]
	v_cndmask_b32_e64 v51, v51, 0, s[6:7]
	v_cndmask_b32_e64 v50, v50, 0, s[6:7]
	s_waitcnt vmcnt(12)
	s_nop 1
	v_mfma_f32_32x32x16_bf16 v[0:15], v[160:163], v[50:53], v[0:15]
	ds_read_b128 v[46:49], v18 offset:704
	s_waitcnt lgkmcnt(2)
	v_cndmask_b32_e64 v23, v23, 0, s[6:7]
	v_cndmask_b32_e64 v22, v22, 0, s[6:7]
	v_cndmask_b32_e64 v21, v21, 0, s[6:7]
	v_cndmask_b32_e64 v20, v20, 0, s[6:7]
	s_waitcnt vmcnt(11)
	s_nop 1
	v_mfma_f32_32x32x16_bf16 v[0:15], v[164:167], v[20:23], v[0:15]
	ds_read_b128 v[50:53], v18 offset:736
	s_waitcnt lgkmcnt(2)
	v_cndmask_b32_e64 v35, v35, 0, s[6:7]
	v_cndmask_b32_e64 v34, v34, 0, s[6:7]
	v_cndmask_b32_e64 v33, v33, 0, s[6:7]
	v_cndmask_b32_e64 v32, v32, 0, s[6:7]
	s_waitcnt vmcnt(10)
	s_nop 1
	v_mfma_f32_32x32x16_bf16 v[0:15], v[168:171], v[32:35], v[0:15]
	ds_read_b128 v[20:23], v18 offset:768
	s_waitcnt lgkmcnt(2)
	v_cndmask_b32_e64 v49, v49, 0, s[6:7]
	v_cndmask_b32_e64 v48, v48, 0, s[6:7]
	v_cndmask_b32_e64 v47, v47, 0, s[6:7]
	v_cndmask_b32_e64 v46, v46, 0, s[6:7]
	s_waitcnt vmcnt(9)
	s_nop 1
	v_mfma_f32_32x32x16_bf16 v[0:15], v[172:175], v[46:49], v[0:15]
	ds_read_b128 v[32:35], v18 offset:800
	s_waitcnt lgkmcnt(2)
	v_cndmask_b32_e64 v53, v53, 0, s[6:7]
	v_cndmask_b32_e64 v52, v52, 0, s[6:7]
	v_cndmask_b32_e64 v51, v51, 0, s[6:7]
	v_cndmask_b32_e64 v50, v50, 0, s[6:7]
	s_waitcnt vmcnt(8)
	s_nop 1
	v_mfma_f32_32x32x16_bf16 v[0:15], v[176:179], v[50:53], v[0:15]
	ds_read_b128 v[46:49], v18 offset:832
	s_waitcnt lgkmcnt(2)
	v_cndmask_b32_e64 v23, v23, 0, s[6:7]
	v_cndmask_b32_e64 v22, v22, 0, s[6:7]
	v_cndmask_b32_e64 v21, v21, 0, s[6:7]
	v_cndmask_b32_e64 v20, v20, 0, s[6:7]
	s_waitcnt vmcnt(7)
	s_nop 1
	v_mfma_f32_32x32x16_bf16 v[0:15], v[180:183], v[20:23], v[0:15]
	ds_read_b128 v[50:53], v18 offset:864
	s_waitcnt lgkmcnt(2)
	v_cndmask_b32_e64 v35, v35, 0, s[6:7]
	v_cndmask_b32_e64 v34, v34, 0, s[6:7]
	v_cndmask_b32_e64 v33, v33, 0, s[6:7]
	v_cndmask_b32_e64 v32, v32, 0, s[6:7]
	s_waitcnt vmcnt(6)
	s_nop 1
	v_mfma_f32_32x32x16_bf16 v[0:15], v[184:187], v[32:35], v[0:15]
	ds_read_b128 v[20:23], v18 offset:896
	s_waitcnt lgkmcnt(2)
	v_cndmask_b32_e64 v49, v49, 0, s[6:7]
	v_cndmask_b32_e64 v48, v48, 0, s[6:7]
	v_cndmask_b32_e64 v47, v47, 0, s[6:7]
	v_cndmask_b32_e64 v46, v46, 0, s[6:7]
	s_waitcnt vmcnt(5)
	s_nop 1
	v_mfma_f32_32x32x16_bf16 v[0:15], v[188:191], v[46:49], v[0:15]
	ds_read_b128 v[32:35], v18 offset:928
	s_waitcnt lgkmcnt(2)
	v_cndmask_b32_e64 v53, v53, 0, s[6:7]
	v_cndmask_b32_e64 v52, v52, 0, s[6:7]
	v_cndmask_b32_e64 v51, v51, 0, s[6:7]
	v_cndmask_b32_e64 v50, v50, 0, s[6:7]
	s_waitcnt vmcnt(4)
	s_nop 1
	v_mfma_f32_32x32x16_bf16 v[0:15], v[192:195], v[50:53], v[0:15]
	ds_read_b128 v[46:49], v18 offset:960
	s_waitcnt lgkmcnt(2)
	v_cndmask_b32_e64 v23, v23, 0, s[6:7]
	v_cndmask_b32_e64 v22, v22, 0, s[6:7]
	v_cndmask_b32_e64 v21, v21, 0, s[6:7]
	v_cndmask_b32_e64 v20, v20, 0, s[6:7]
	s_waitcnt vmcnt(3)
	s_nop 1
	v_mfma_f32_32x32x16_bf16 v[0:15], v[196:199], v[20:23], v[0:15]
	ds_read_b128 v[50:53], v18 offset:992
	s_waitcnt lgkmcnt(2)
	v_cndmask_b32_e64 v35, v35, 0, s[6:7]
	v_cndmask_b32_e64 v34, v34, 0, s[6:7]
	v_cndmask_b32_e64 v33, v33, 0, s[6:7]
	v_cndmask_b32_e64 v32, v32, 0, s[6:7]
	s_waitcnt vmcnt(2)
	s_nop 1
	v_mfma_f32_32x32x16_bf16 v[0:15], v[200:203], v[32:35], v[0:15]
	s_waitcnt lgkmcnt(1)
	v_cndmask_b32_e64 v49, v49, 0, s[6:7]
	v_cndmask_b32_e64 v48, v48, 0, s[6:7]
	v_cndmask_b32_e64 v47, v47, 0, s[6:7]
	v_cndmask_b32_e64 v46, v46, 0, s[6:7]
	s_waitcnt vmcnt(1)
	s_nop 1
	v_mfma_f32_32x32x16_bf16 v[0:15], v[204:207], v[46:49], v[0:15]
	s_waitcnt lgkmcnt(0)
	v_cndmask_b32_e64 v53, v53, 0, s[6:7]
	v_cndmask_b32_e64 v52, v52, 0, s[6:7]
	v_cndmask_b32_e64 v51, v51, 0, s[6:7]
	v_cndmask_b32_e64 v50, v50, 0, s[6:7]
	s_waitcnt vmcnt(0)
	s_nop 1
	v_mfma_f32_32x32x16_bf16 v[0:15], v[208:211], v[50:53], v[0:15]
	v_add_u32_e32 v18, 0x400, v18
	s_cbranch_scc0 .LBB0_462
	s_waitcnt lgkmcnt(0)
	s_and_saveexec_b64 s[90:91], s[8:9]
	s_cbranch_execz .LBB0_458
	global_load_dword v31, v[26:27], off
	ds_read_b128 v[20:23], v40 offset:16512
	ds_read_b128 v[16:19], v40 offset:16544
	s_ashr_i32 s10, s3, 4
	s_and_b32 s11, s20, 0xfe0
	v_and_or_b32 v34, s10, -8, v36
	v_or_b32_e32 v24, s11, v39
	v_mov_b64_e32 v[32:33], s[80:81]
	v_ashrrev_i32_e32 v35, 31, v34
	v_lshlrev_b64 v[34:35], 14, v[34:35]
	v_lshl_add_u64 v[34:35], s[26:27], 0, v[34:35]
	v_lshlrev_b32_e32 v24, 2, v24
	s_waitcnt vmcnt(0) lgkmcnt(1)
	v_fma_f32 v0, v0, v20, v31
	v_mul_f32_e64 v20, |v0|, s16
	v_fma_f32 v1, v1, v21, v31
	v_exp_f32_e32 v45, v20
	v_mul_f32_e64 v21, |v1|, s16
	v_exp_f32_e32 v80, v21
	v_fma_f32 v2, v2, v22, v31
	v_add_f32_e32 v48, 1.0, v45
	v_frexp_mant_f32_e32 v51, v48
	v_cvt_f64_f32_e32 v[20:21], v48
	v_add_f32_e32 v49, 1.0, v80
	v_frexp_exp_i32_f64_e32 v20, v[20:21]
	v_cmp_gt_f32_e64 s[10:11], s17, v51
	v_add_f32_e32 v50, -1.0, v48
	v_add_f32_e32 v52, -1.0, v49
	v_frexp_mant_f32_e32 v53, v49
	v_cvt_f64_f32_e32 v[46:47], v49
	v_subbrev_co_u32_e64 v20, s[10:11], 0, v20, s[10:11]
	v_sub_f32_e32 v54, v50, v48
	v_sub_f32_e32 v21, v52, v49
	v_frexp_exp_i32_f64_e32 v46, v[46:47]
	v_cmp_gt_f32_e64 s[10:11], s17, v53
	v_sub_f32_e32 v50, v45, v50
	v_sub_f32_e32 v52, v80, v52
	v_add_f32_e32 v47, 1.0, v54
	v_add_f32_e32 v21, 1.0, v21
	v_subbrev_co_u32_e64 v46, s[10:11], 0, v46, s[10:11]
	v_add_f32_e32 v47, v50, v47
	v_sub_u32_e32 v50, 0, v20
	v_add_f32_e32 v51, v52, v21
	v_sub_u32_e32 v52, 0, v46
	v_cvt_f32_i32_e32 v21, v46
	v_cvt_f32_i32_e32 v20, v20
	v_ldexp_f32 v46, v48, v50
	v_ldexp_f32 v48, v47, v50
	v_ldexp_f32 v47, v49, v52
	v_ldexp_f32 v49, v51, v52
	v_pk_add_f32 v[50:51], v[46:47], 1.0 op_sel_hi:[1,0]
	v_pk_add_f32 v[52:53], v[46:47], -1.0 op_sel_hi:[1,0]
	v_pk_add_f32 v[54:55], v[50:51], -1.0 op_sel_hi:[1,0]
	v_pk_add_f32 v[56:57], v[52:53], 1.0 op_sel_hi:[1,0]
	v_pk_add_f32 v[54:55], v[46:47], v[54:55] neg_lo:[0,1] neg_hi:[0,1]
	v_pk_add_f32 v[46:47], v[46:47], v[56:57] neg_lo:[0,1] neg_hi:[0,1]
	v_pk_mul_f32 v[56:57], v[20:21], s[86:87] op_sel_hi:[1,0]
	v_pk_add_f32 v[54:55], v[48:49], v[54:55]
	v_pk_add_f32 v[46:47], v[48:49], v[46:47]
	v_pk_fma_f32 v[48:49], v[20:21], s[86:87], v[56:57] op_sel_hi:[1,0,1] neg_lo:[0,0,1] neg_hi:[0,0,1]
	v_pk_add_f32 v[62:63], v[50:51], v[54:55]
	v_pk_fma_f32 v[20:21], v[20:21], s[88:89], v[48:49] op_sel_hi:[1,0,1]
	v_rcp_f32_e32 v48, v62
	v_rcp_f32_e32 v49, v63
	v_pk_add_f32 v[64:65], v[52:53], v[46:47]
	v_pk_add_f32 v[50:51], v[62:63], v[50:51] neg_lo:[0,1] neg_hi:[0,1]
	v_pk_add_f32 v[52:53], v[64:65], v[52:53] neg_lo:[0,1] neg_hi:[0,1]
	v_pk_add_f32 v[50:51], v[54:55], v[50:51] neg_lo:[0,1] neg_hi:[0,1]
	v_pk_mul_f32 v[54:55], v[64:65], v[48:49]
	v_pk_add_f32 v[46:47], v[46:47], v[52:53] neg_lo:[0,1] neg_hi:[0,1]
	v_pk_mul_f32 v[72:73], v[62:63], v[54:55]
	v_pk_add_f32 v[66:67], v[56:57], v[20:21]
	v_pk_fma_f32 v[74:75], v[54:55], v[62:63], v[72:73] neg_lo:[0,0,1] neg_hi:[0,0,1]
	v_mov_b32_e32 v58, v56
	v_pk_fma_f32 v[74:75], v[54:55], v[50:51], v[74:75]
	v_mov_b32_e32 v68, v20
	v_pk_add_f32 v[76:77], v[72:73], v[74:75]
	v_mov_b32_e32 v61, v57
	v_pk_add_f32 v[78:79], v[64:65], v[76:77] neg_lo:[0,1] neg_hi:[0,1]
	v_pk_add_f32 v[72:73], v[76:77], v[72:73] neg_lo:[0,1] neg_hi:[0,1]
	v_pk_add_f32 v[64:65], v[64:65], v[78:79] neg_lo:[0,1] neg_hi:[0,1]
	v_pk_add_f32 v[72:73], v[72:73], v[74:75] neg_lo:[0,1] neg_hi:[0,1]
	v_pk_add_f32 v[64:65], v[64:65], v[76:77] neg_lo:[0,1] neg_hi:[0,1]
	v_mov_b32_e32 v53, v67
	v_pk_add_f32 v[46:47], v[46:47], v[64:65]
	v_mov_b32_e32 v60, v66
	v_pk_add_f32 v[46:47], v[72:73], v[46:47]
	v_mov_b32_e32 v71, v21
	v_pk_add_f32 v[64:65], v[78:79], v[46:47]
	v_cmp_neq_f32_e64 s[10:11], s18, v45
	v_pk_mul_f32 v[72:73], v[48:49], v[64:65]
	v_pk_add_f32 v[74:75], v[78:79], v[64:65] neg_lo:[0,1] neg_hi:[0,1]
	v_pk_mul_f32 v[76:77], v[62:63], v[72:73]
	v_pk_add_f32 v[46:47], v[46:47], v[74:75]
	v_pk_fma_f32 v[62:63], v[72:73], v[62:63], v[76:77] neg_lo:[0,0,1] neg_hi:[0,0,1]
	v_pk_add_f32 v[74:75], v[54:55], v[72:73]
	v_pk_fma_f32 v[50:51], v[72:73], v[50:51], v[62:63]
	v_pk_add_f32 v[54:55], v[74:75], v[54:55] neg_lo:[0,1] neg_hi:[0,1]
	v_pk_add_f32 v[62:63], v[76:77], v[50:51]
	v_pk_add_f32 v[54:55], v[72:73], v[54:55] neg_lo:[0,1] neg_hi:[0,1]
	v_pk_add_f32 v[72:73], v[62:63], v[76:77] neg_lo:[0,1] neg_hi:[0,1]
	v_pk_add_f32 v[76:77], v[64:65], v[62:63] neg_lo:[0,1] neg_hi:[0,1]
	v_pk_add_f32 v[50:51], v[72:73], v[50:51] neg_lo:[0,1] neg_hi:[0,1]
	v_pk_add_f32 v[64:65], v[64:65], v[76:77] neg_lo:[0,1] neg_hi:[0,1]
	v_mul_f32_e64 v22, |v2|, s16
	v_pk_add_f32 v[62:63], v[64:65], v[62:63] neg_lo:[0,1] neg_hi:[0,1]
	v_min_f32_e32 v0, 0, v0
	v_pk_add_f32 v[46:47], v[46:47], v[62:63]
	v_min_f32_e32 v1, 0, v1
	v_pk_add_f32 v[46:47], v[50:51], v[46:47]
	v_fma_f32 v3, v3, v23, v31
	v_pk_add_f32 v[46:47], v[76:77], v[46:47]
	s_waitcnt lgkmcnt(0)
	v_fma_f32 v4, v4, v16, v31
	v_pk_mul_f32 v[46:47], v[48:49], v[46:47]
	v_mul_f32_e64 v16, |v4|, s16
	v_pk_add_f32 v[46:47], v[54:55], v[46:47]
	v_min_f32_e32 v2, 0, v2
	v_pk_add_f32 v[48:49], v[74:75], v[46:47]
	v_fma_f32 v5, v5, v17, v31
	v_pk_add_f32 v[50:51], v[48:49], v[74:75] neg_lo:[0,1] neg_hi:[0,1]
	v_pk_mul_f32 v[62:63], v[48:49], v[48:49]
	v_pk_add_f32 v[46:47], v[46:47], v[50:51] neg_lo:[0,1] neg_hi:[0,1]
	v_pk_fma_f32 v[50:51], v[62:63], s[82:83], v[32:33] op_sel_hi:[1,0,0]
	v_ldexp_f32 v54, v48, 1
	v_ldexp_f32 v55, v49, 1
	v_pk_mul_f32 v[48:49], v[48:49], v[62:63]
	v_pk_fma_f32 v[50:51], v[62:63], v[50:51], s[84:85] op_sel_hi:[1,1,0]
	v_ldexp_f32 v69, v47, 1
	v_pk_mul_f32 v[48:49], v[48:49], v[50:51]
	v_ldexp_f32 v46, v46, 1
	v_pk_add_f32 v[50:51], v[54:55], v[48:49]
	v_mov_b32_e32 v47, v69
	v_pk_add_f32 v[54:55], v[50:51], v[54:55] neg_lo:[0,1] neg_hi:[0,1]
	v_fma_f32 v7, v7, v19, v31
	v_pk_add_f32 v[48:49], v[48:49], v[54:55] neg_lo:[0,1] neg_hi:[0,1]
	s_nop 0
	v_pk_add_f32 v[54:55], v[46:47], v[48:49]
	v_mov_b32_e32 v59, v49
	v_mov_b32_e32 v49, v51
	v_mov_b32_e32 v47, v55
	v_pk_add_f32 v[62:63], v[50:51], v[54:55]
	v_pk_add_f32 v[46:47], v[46:47], v[48:49]
	v_pk_add_f32 v[48:49], v[66:67], v[62:63]
	v_pk_add_f32 v[58:59], v[58:59], v[68:69]
	v_mov_b32_e32 v64, v62
	v_mov_b32_e32 v65, v49
	v_mov_b32_e32 v68, v50
	v_mov_b32_e32 v69, v67
	v_pk_add_f32 v[64:65], v[64:65], v[68:69] neg_lo:[0,1] neg_hi:[0,1]
	v_mov_b32_e32 v52, v48
	v_mov_b32_e32 v68, v66
	v_mov_b32_e32 v69, v49
	v_mov_b32_e32 v57, v65
	v_mov_b32_e32 v70, v62
	v_pk_add_f32 v[52:53], v[52:53], v[60:61] neg_lo:[0,1] neg_hi:[0,1]
	v_pk_add_f32 v[56:57], v[68:69], v[56:57] neg_lo:[0,1] neg_hi:[0,1]
	v_pk_add_f32 v[60:61], v[70:71], v[52:53] neg_lo:[0,1] neg_hi:[0,1]
	v_mov_b32_e32 v68, v56
	v_mov_b32_e32 v69, v53
	v_mov_b32_e32 v70, v48
	v_mov_b32_e32 v71, v63
	v_mov_b32_e32 v53, v51
	v_pk_add_f32 v[68:69], v[20:21], v[68:69] neg_lo:[0,1] neg_hi:[0,1]
	v_pk_add_f32 v[52:53], v[70:71], v[52:53] neg_lo:[0,1] neg_hi:[0,1]
	v_mov_b32_e32 v21, v67
	v_pk_add_f32 v[50:51], v[62:63], v[50:51] neg_lo:[0,1] neg_hi:[0,1]
	v_pk_add_f32 v[52:53], v[58:59], v[52:53] neg_lo:[0,1] neg_hi:[0,1]
	v_pk_add_f32 v[20:21], v[20:21], v[56:57] neg_lo:[0,1] neg_hi:[0,1]
	v_pk_add_f32 v[46:47], v[46:47], v[64:65] neg_lo:[0,1] neg_hi:[0,1]
	v_pk_add_f32 v[50:51], v[54:55], v[50:51] neg_lo:[0,1] neg_hi:[0,1]
	v_pk_add_f32 v[54:55], v[46:47], v[20:21]
	v_mov_b32_e32 v21, v61
	v_mov_b32_e32 v47, v53
	v_pk_add_f32 v[56:57], v[60:61], v[52:53]
	v_pk_add_f32 v[46:47], v[20:21], v[46:47]
	v_mov_b32_e32 v52, v54
	v_pk_add_f32 v[46:47], v[46:47], v[68:69] neg_lo:[0,1] neg_hi:[0,1]
	v_mov_b32_e32 v53, v57
	v_pk_add_f32 v[52:53], v[52:53], v[46:47] neg_lo:[0,1] neg_hi:[0,1]
	v_pk_add_f32 v[46:47], v[50:51], v[46:47] neg_lo:[0,1] neg_hi:[0,1]
	v_pk_add_f32 v[20:21], v[20:21], v[52:53] neg_lo:[0,1] neg_hi:[0,1]
	v_exp_f32_e32 v70, v22
	v_pk_add_f32 v[20:21], v[46:47], v[20:21]
	v_pk_add_f32 v[46:47], v[56:57], v[54:55]
	v_add_f32_e32 v22, 1.0, v70
	v_pk_add_f32 v[50:51], v[48:49], v[46:47]
	s_nop 0
	v_pk_add_f32 v[48:49], v[50:51], v[48:49] neg_lo:[0,1] neg_hi:[0,1]
	s_nop 0
	v_pk_add_f32 v[46:47], v[46:47], v[48:49] neg_lo:[0,1] neg_hi:[0,1]
	s_nop 0
	v_pk_add_f32 v[20:21], v[20:21], v[46:47]
	v_frexp_mant_f32_e32 v46, v22
	v_pk_add_f32 v[20:21], v[50:51], v[20:21]
	s_nop 0
	v_cndmask_b32_e64 v20, v42, v20, s[10:11]
	v_cmp_neq_f32_e64 s[10:11], s18, v80
	s_nop 1
	v_cndmask_b32_e64 v21, v42, v21, s[10:11]
	v_cmp_ngt_f32_e64 s[10:11], -1.0, v80
	s_nop 1
	v_cndmask_b32_e64 v21, v43, v21, s[10:11]
	v_cmp_ngt_f32_e64 s[10:11], -1.0, v45
	s_nop 1
	v_cndmask_b32_e64 v20, v43, v20, s[10:11]
	v_cmp_neq_f32_e64 s[10:11], -1.0, v45
	s_nop 1
	v_cndmask_b32_e64 v20, v44, v20, s[10:11]
	v_cmp_neq_f32_e64 s[10:11], -1.0, v80
	s_nop 1
	v_cndmask_b32_e64 v21, v44, v21, s[10:11]
	v_cmp_lt_f32_e64 s[10:11], |v80|, s19
	s_nop 1
	v_cndmask_b32_e64 v21, v21, v80, s[10:11]
	v_cmp_lt_f32_e64 s[10:11], |v45|, s19
	s_nop 1
	v_cndmask_b32_e64 v20, v20, v45, s[10:11]
	v_pk_add_f32 v[0:1], v[0:1], v[20:21] neg_lo:[0,1] neg_hi:[0,1]
	v_add_f32_e32 v20, -1.0, v22
	v_sub_f32_e32 v21, v20, v22
	v_add_f32_e32 v21, 1.0, v21
	v_sub_f32_e32 v20, v70, v20
	v_add_f32_e32 v45, v20, v21
	v_cvt_f64_f32_e32 v[20:21], v22
	v_frexp_exp_i32_f64_e32 v20, v[20:21]
	v_cmp_gt_f32_e64 s[10:11], s17, v46
	s_nop 1
	v_subbrev_co_u32_e64 v62, s[10:11], 0, v20, s[10:11]
	v_sub_u32_e32 v20, 0, v62
	v_ldexp_f32 v22, v22, v20
	v_ldexp_f32 v46, v45, v20
	v_mul_f32_e64 v20, |v3|, s16
	v_exp_f32_e32 v45, v20
	v_lshl_add_u64 v[20:21], v[34:35], 0, v[24:25]
	v_min_f32_e32 v3, 0, v3
	v_add_f32_e32 v23, 1.0, v45
	v_add_f32_e32 v24, -1.0, v23
	v_sub_f32_e32 v34, v24, v23
	v_add_f32_e32 v34, 1.0, v34
	v_sub_f32_e32 v24, v45, v24
	v_add_f32_e32 v24, v24, v34
	v_frexp_mant_f32_e32 v47, v23
	v_cvt_f64_f32_e32 v[34:35], v23
	v_frexp_exp_i32_f64_e32 v34, v[34:35]
	v_cmp_gt_f32_e64 s[10:11], s17, v47
	s_nop 1
	v_subbrev_co_u32_e64 v63, s[10:11], 0, v34, s[10:11]
	v_sub_u32_e32 v34, 0, v63
	v_ldexp_f32 v23, v23, v34
	v_ldexp_f32 v47, v24, v34
	v_pk_add_f32 v[34:35], v[22:23], 1.0 op_sel_hi:[1,0]
	v_pk_add_f32 v[54:55], v[22:23], -1.0 op_sel_hi:[1,0]
	v_pk_add_f32 v[48:49], v[34:35], -1.0 op_sel_hi:[1,0]
	v_pk_add_f32 v[56:57], v[54:55], 1.0 op_sel_hi:[1,0]
	v_pk_add_f32 v[48:49], v[22:23], v[48:49] neg_lo:[0,1] neg_hi:[0,1]
	v_pk_add_f32 v[22:23], v[22:23], v[56:57] neg_lo:[0,1] neg_hi:[0,1]
	v_pk_add_f32 v[48:49], v[46:47], v[48:49]
	v_pk_add_f32 v[22:23], v[46:47], v[22:23]
	v_pk_add_f32 v[50:51], v[34:35], v[48:49]
	v_pk_add_f32 v[46:47], v[54:55], v[22:23]
	v_rcp_f32_e32 v52, v50
	v_rcp_f32_e32 v53, v51
	v_pk_add_f32 v[34:35], v[50:51], v[34:35] neg_lo:[0,1] neg_hi:[0,1]
	v_pk_add_f32 v[54:55], v[46:47], v[54:55] neg_lo:[0,1] neg_hi:[0,1]
	v_pk_add_f32 v[34:35], v[48:49], v[34:35] neg_lo:[0,1] neg_hi:[0,1]
	v_pk_mul_f32 v[48:49], v[46:47], v[52:53]
	v_pk_add_f32 v[22:23], v[22:23], v[54:55] neg_lo:[0,1] neg_hi:[0,1]
	v_pk_mul_f32 v[54:55], v[50:51], v[48:49]
	v_cmp_neq_f32_e64 s[10:11], s18, v70
	v_pk_fma_f32 v[56:57], v[48:49], v[50:51], v[54:55] neg_lo:[0,0,1] neg_hi:[0,0,1]
	v_exp_f32_e32 v24, v16
	v_pk_fma_f32 v[56:57], v[48:49], v[34:35], v[56:57]
	s_nop 0
	v_pk_add_f32 v[58:59], v[54:55], v[56:57]
	s_nop 0
	v_pk_add_f32 v[60:61], v[46:47], v[58:59] neg_lo:[0,1] neg_hi:[0,1]
	v_pk_add_f32 v[54:55], v[58:59], v[54:55] neg_lo:[0,1] neg_hi:[0,1]
	v_pk_add_f32 v[46:47], v[46:47], v[60:61] neg_lo:[0,1] neg_hi:[0,1]
	s_nop 0
	v_pk_add_f32 v[46:47], v[46:47], v[58:59] neg_lo:[0,1] neg_hi:[0,1]
	s_nop 0
	v_pk_add_f32 v[22:23], v[22:23], v[46:47]
	v_pk_add_f32 v[46:47], v[54:55], v[56:57] neg_lo:[0,1] neg_hi:[0,1]
	s_nop 0
	v_pk_add_f32 v[22:23], v[46:47], v[22:23]
	s_nop 0
	v_pk_add_f32 v[46:47], v[60:61], v[22:23]
	s_nop 0
	v_pk_mul_f32 v[54:55], v[52:53], v[46:47]
	s_nop 0
	v_pk_mul_f32 v[56:57], v[50:51], v[54:55]
	s_nop 0
	v_pk_fma_f32 v[50:51], v[54:55], v[50:51], v[56:57] neg_lo:[0,0,1] neg_hi:[0,0,1]
	s_nop 0
	v_pk_fma_f32 v[34:35], v[54:55], v[34:35], v[50:51]
	v_pk_add_f32 v[50:51], v[60:61], v[46:47] neg_lo:[0,1] neg_hi:[0,1]
	s_nop 0
	v_pk_add_f32 v[22:23], v[22:23], v[50:51]
	v_pk_add_f32 v[50:51], v[56:57], v[34:35]
	s_nop 0
	v_pk_add_f32 v[58:59], v[46:47], v[50:51] neg_lo:[0,1] neg_hi:[0,1]
	v_pk_add_f32 v[56:57], v[50:51], v[56:57] neg_lo:[0,1] neg_hi:[0,1]
	v_pk_add_f32 v[46:47], v[46:47], v[58:59] neg_lo:[0,1] neg_hi:[0,1]
	v_pk_add_f32 v[34:35], v[56:57], v[34:35] neg_lo:[0,1] neg_hi:[0,1]
	v_pk_add_f32 v[46:47], v[46:47], v[50:51] neg_lo:[0,1] neg_hi:[0,1]
	s_nop 0
	v_pk_add_f32 v[22:23], v[22:23], v[46:47]
	s_nop 0
	v_pk_add_f32 v[22:23], v[34:35], v[22:23]
	v_pk_add_f32 v[34:35], v[48:49], v[54:55]
	v_pk_add_f32 v[22:23], v[58:59], v[22:23]
	v_pk_add_f32 v[46:47], v[34:35], v[48:49] neg_lo:[0,1] neg_hi:[0,1]
	v_pk_mul_f32 v[22:23], v[52:53], v[22:23]
	v_pk_add_f32 v[46:47], v[54:55], v[46:47] neg_lo:[0,1] neg_hi:[0,1]
	v_cvt_f32_i32_e32 v53, v63
	v_pk_add_f32 v[22:23], v[46:47], v[22:23]
	v_cvt_f32_i32_e32 v52, v62
	v_pk_add_f32 v[46:47], v[34:35], v[22:23]
	s_nop 0
	v_pk_mul_f32 v[48:49], v[46:47], v[46:47]
	v_pk_add_f32 v[34:35], v[46:47], v[34:35] neg_lo:[0,1] neg_hi:[0,1]
	v_pk_fma_f32 v[50:51], v[48:49], s[82:83], v[32:33] op_sel_hi:[1,0,0]
	v_pk_add_f32 v[22:23], v[22:23], v[34:35] neg_lo:[0,1] neg_hi:[0,1]
	v_ldexp_f32 v34, v46, 1
	v_pk_fma_f32 v[50:51], v[48:49], v[50:51], s[84:85] op_sel_hi:[1,1,0]
	v_ldexp_f32 v35, v47, 1
	v_pk_mul_f32 v[46:47], v[46:47], v[48:49]
	v_pk_mul_f32 v[48:49], v[52:53], s[86:87] op_sel_hi:[1,0]
	v_pk_mul_f32 v[46:47], v[46:47], v[50:51]
	v_pk_fma_f32 v[56:57], v[52:53], s[86:87], v[48:49] op_sel_hi:[1,0,1] neg_lo:[0,0,1] neg_hi:[0,0,1]
	v_pk_add_f32 v[50:51], v[34:35], v[46:47]
	v_ldexp_f32 v55, v23, 1
	v_pk_add_f32 v[34:35], v[50:51], v[34:35] neg_lo:[0,1] neg_hi:[0,1]
	v_pk_fma_f32 v[52:53], v[52:53], s[88:89], v[56:57] op_sel_hi:[1,0,1]
	v_pk_add_f32 v[34:35], v[46:47], v[34:35] neg_lo:[0,1] neg_hi:[0,1]
	v_ldexp_f32 v22, v22, 1
	v_mov_b32_e32 v46, v48
	v_mov_b32_e32 v47, v35
	v_mov_b32_e32 v54, v52
	v_mov_b32_e32 v23, v55
	v_pk_add_f32 v[46:47], v[46:47], v[54:55]
	v_pk_add_f32 v[54:55], v[22:23], v[34:35]
	v_mov_b32_e32 v35, v51
	v_mov_b32_e32 v23, v55
	v_pk_add_f32 v[56:57], v[48:49], v[52:53]
	v_pk_add_f32 v[22:23], v[22:23], v[34:35]
	v_pk_add_f32 v[34:35], v[50:51], v[54:55]
	v_mov_b32_e32 v66, v50
	v_pk_add_f32 v[58:59], v[56:57], v[34:35]
	v_mov_b32_e32 v64, v34
	v_mov_b32_e32 v65, v59
	v_mov_b32_e32 v67, v57
	v_pk_add_f32 v[64:65], v[64:65], v[66:67] neg_lo:[0,1] neg_hi:[0,1]
	v_mov_b32_e32 v60, v58
	v_mov_b32_e32 v61, v57
	v_mov_b32_e32 v62, v56
	v_mov_b32_e32 v63, v49
	v_mov_b32_e32 v66, v56
	v_mov_b32_e32 v67, v59
	v_mov_b32_e32 v49, v65
	v_pk_add_f32 v[60:61], v[60:61], v[62:63] neg_lo:[0,1] neg_hi:[0,1]
	v_mov_b32_e32 v62, v34
	v_mov_b32_e32 v63, v53
	v_pk_add_f32 v[48:49], v[66:67], v[48:49] neg_lo:[0,1] neg_hi:[0,1]
	v_pk_add_f32 v[62:63], v[62:63], v[60:61] neg_lo:[0,1] neg_hi:[0,1]
	v_mov_b32_e32 v66, v48
	v_mov_b32_e32 v67, v61
	v_mov_b32_e32 v68, v58
	v_mov_b32_e32 v69, v35
	v_mov_b32_e32 v61, v51
	v_pk_add_f32 v[66:67], v[52:53], v[66:67] neg_lo:[0,1] neg_hi:[0,1]
	v_pk_add_f32 v[60:61], v[68:69], v[60:61] neg_lo:[0,1] neg_hi:[0,1]
	v_mov_b32_e32 v53, v57
	v_pk_add_f32 v[46:47], v[46:47], v[60:61] neg_lo:[0,1] neg_hi:[0,1]
	v_pk_add_f32 v[48:49], v[52:53], v[48:49] neg_lo:[0,1] neg_hi:[0,1]
	v_pk_add_f32 v[22:23], v[22:23], v[64:65] neg_lo:[0,1] neg_hi:[0,1]
	v_pk_add_f32 v[34:35], v[34:35], v[50:51] neg_lo:[0,1] neg_hi:[0,1]
	v_pk_add_f32 v[50:51], v[22:23], v[48:49]
	v_mov_b32_e32 v49, v63
	v_mov_b32_e32 v23, v47
	v_pk_add_f32 v[52:53], v[62:63], v[46:47]
	v_pk_add_f32 v[22:23], v[48:49], v[22:23]
	v_mov_b32_e32 v46, v50
	v_pk_add_f32 v[22:23], v[22:23], v[66:67] neg_lo:[0,1] neg_hi:[0,1]
	v_mov_b32_e32 v47, v53
	v_pk_add_f32 v[34:35], v[54:55], v[34:35] neg_lo:[0,1] neg_hi:[0,1]
	v_pk_add_f32 v[46:47], v[46:47], v[22:23] neg_lo:[0,1] neg_hi:[0,1]
	v_pk_add_f32 v[22:23], v[34:35], v[22:23] neg_lo:[0,1] neg_hi:[0,1]
	v_pk_add_f32 v[46:47], v[48:49], v[46:47] neg_lo:[0,1] neg_hi:[0,1]
	v_pk_add_f32 v[34:35], v[52:53], v[50:51]
	v_pk_add_f32 v[22:23], v[22:23], v[46:47]
	v_pk_add_f32 v[46:47], v[58:59], v[34:35]
	s_nop 0
	v_pk_add_f32 v[48:49], v[46:47], v[58:59] neg_lo:[0,1] neg_hi:[0,1]
	s_nop 0
	v_pk_add_f32 v[34:35], v[34:35], v[48:49] neg_lo:[0,1] neg_hi:[0,1]
	s_nop 0
	v_pk_add_f32 v[22:23], v[22:23], v[34:35]
	s_nop 0
	v_pk_add_f32 v[22:23], v[46:47], v[22:23]
	s_nop 0
	v_cndmask_b32_e64 v22, v42, v22, s[10:11]
	v_cmp_neq_f32_e64 s[10:11], s18, v45
	s_nop 1
	v_cndmask_b32_e64 v23, v42, v23, s[10:11]
	v_cmp_ngt_f32_e64 s[10:11], -1.0, v45
	s_nop 1
	v_cndmask_b32_e64 v23, v43, v23, s[10:11]
	v_cmp_ngt_f32_e64 s[10:11], -1.0, v70
	s_nop 1
	v_cndmask_b32_e64 v22, v43, v22, s[10:11]
	v_cmp_neq_f32_e64 s[10:11], -1.0, v70
	s_nop 1
	v_cndmask_b32_e64 v22, v44, v22, s[10:11]
	v_cmp_neq_f32_e64 s[10:11], -1.0, v45
	s_nop 1
	v_cndmask_b32_e64 v23, v44, v23, s[10:11]
	v_cmp_lt_f32_e64 s[10:11], |v45|, s19
	s_nop 1
	v_cndmask_b32_e64 v23, v23, v45, s[10:11]
	v_cmp_lt_f32_e64 s[10:11], |v70|, s19
	s_nop 1
	v_cndmask_b32_e64 v22, v22, v70, s[10:11]
	v_pk_add_f32 v[2:3], v[2:3], v[22:23] neg_lo:[0,1] neg_hi:[0,1]
	global_store_dwordx4 v[20:21], v[0:3], off
	s_nop 1
	v_add_f32_e32 v1, 1.0, v24
	v_add_f32_e32 v2, -1.0, v1
	v_sub_f32_e32 v3, v2, v1
	v_add_f32_e32 v3, 1.0, v3
	v_sub_f32_e32 v2, v24, v2
	v_min_f32_e32 v0, 0, v4
	v_add_f32_e32 v4, v2, v3
	v_frexp_mant_f32_e32 v16, v1
	v_cvt_f64_f32_e32 v[2:3], v1
	v_frexp_exp_i32_f64_e32 v2, v[2:3]
	v_cmp_gt_f32_e64 s[10:11], s17, v16
	s_nop 1
	v_subbrev_co_u32_e64 v45, s[10:11], 0, v2, s[10:11]
	v_mul_f32_e64 v2, |v5|, s16
	v_exp_f32_e32 v64, v2
	v_sub_u32_e32 v3, 0, v45
	v_ldexp_f32 v2, v1, v3
	v_ldexp_f32 v4, v4, v3
	v_add_f32_e32 v3, 1.0, v64
	v_min_f32_e32 v1, 0, v5
	v_add_f32_e32 v5, -1.0, v3
	v_sub_f32_e32 v16, v5, v3
	v_add_f32_e32 v16, 1.0, v16
	v_sub_f32_e32 v5, v64, v5
	v_add_f32_e32 v5, v5, v16
	v_frexp_mant_f32_e32 v22, v3
	v_cvt_f64_f32_e32 v[16:17], v3
	v_frexp_exp_i32_f64_e32 v16, v[16:17]
	v_cmp_gt_f32_e64 s[10:11], s17, v22
	s_nop 1
	v_subbrev_co_u32_e64 v56, s[10:11], 0, v16, s[10:11]
	v_sub_u32_e32 v16, 0, v56
	v_ldexp_f32 v3, v3, v16
	v_ldexp_f32 v5, v5, v16
	v_pk_add_f32 v[16:17], v[2:3], 1.0 op_sel_hi:[1,0]
	v_pk_add_f32 v[48:49], v[2:3], -1.0 op_sel_hi:[1,0]
	v_pk_add_f32 v[22:23], v[16:17], -1.0 op_sel_hi:[1,0]
	v_pk_add_f32 v[50:51], v[48:49], 1.0 op_sel_hi:[1,0]
	v_pk_add_f32 v[22:23], v[2:3], v[22:23] neg_lo:[0,1] neg_hi:[0,1]
	v_pk_add_f32 v[2:3], v[2:3], v[50:51] neg_lo:[0,1] neg_hi:[0,1]
	v_pk_add_f32 v[22:23], v[4:5], v[22:23]
	v_pk_add_f32 v[2:3], v[4:5], v[2:3]
	v_pk_add_f32 v[34:35], v[16:17], v[22:23]
	v_pk_add_f32 v[4:5], v[48:49], v[2:3]
	v_rcp_f32_e32 v46, v34
	v_rcp_f32_e32 v47, v35
	v_pk_add_f32 v[16:17], v[34:35], v[16:17] neg_lo:[0,1] neg_hi:[0,1]
	v_pk_add_f32 v[48:49], v[4:5], v[48:49] neg_lo:[0,1] neg_hi:[0,1]
	v_pk_add_f32 v[16:17], v[22:23], v[16:17] neg_lo:[0,1] neg_hi:[0,1]
	v_pk_mul_f32 v[22:23], v[4:5], v[46:47]
	v_pk_add_f32 v[2:3], v[2:3], v[48:49] neg_lo:[0,1] neg_hi:[0,1]
	v_pk_mul_f32 v[48:49], v[34:35], v[22:23]
	v_cmp_neq_f32_e64 s[10:11], s18, v24
	v_pk_fma_f32 v[50:51], v[22:23], v[34:35], v[48:49] neg_lo:[0,0,1] neg_hi:[0,0,1]
	s_nop 0
	v_pk_fma_f32 v[50:51], v[22:23], v[16:17], v[50:51]
	s_nop 0
	v_pk_add_f32 v[52:53], v[48:49], v[50:51]
	s_nop 0
	v_pk_add_f32 v[54:55], v[4:5], v[52:53] neg_lo:[0,1] neg_hi:[0,1]
	v_pk_add_f32 v[48:49], v[52:53], v[48:49] neg_lo:[0,1] neg_hi:[0,1]
	v_pk_add_f32 v[4:5], v[4:5], v[54:55] neg_lo:[0,1] neg_hi:[0,1]
	s_nop 0
	v_pk_add_f32 v[4:5], v[4:5], v[52:53] neg_lo:[0,1] neg_hi:[0,1]
	s_nop 0
	v_pk_add_f32 v[2:3], v[2:3], v[4:5]
	v_pk_add_f32 v[4:5], v[48:49], v[50:51] neg_lo:[0,1] neg_hi:[0,1]
	s_nop 0
	v_pk_add_f32 v[2:3], v[4:5], v[2:3]
	s_nop 0
	v_pk_add_f32 v[4:5], v[54:55], v[2:3]
	s_nop 0
	v_pk_mul_f32 v[48:49], v[46:47], v[4:5]
	s_nop 0
	v_pk_mul_f32 v[50:51], v[34:35], v[48:49]
	s_nop 0
	v_pk_fma_f32 v[34:35], v[48:49], v[34:35], v[50:51] neg_lo:[0,0,1] neg_hi:[0,0,1]
	s_nop 0
	v_pk_fma_f32 v[16:17], v[48:49], v[16:17], v[34:35]
	v_pk_add_f32 v[34:35], v[54:55], v[4:5] neg_lo:[0,1] neg_hi:[0,1]
	s_nop 0
	v_pk_add_f32 v[2:3], v[2:3], v[34:35]
	v_pk_add_f32 v[34:35], v[50:51], v[16:17]
	s_nop 0
	v_pk_add_f32 v[52:53], v[4:5], v[34:35] neg_lo:[0,1] neg_hi:[0,1]
	v_pk_add_f32 v[50:51], v[34:35], v[50:51] neg_lo:[0,1] neg_hi:[0,1]
	v_pk_add_f32 v[4:5], v[4:5], v[52:53] neg_lo:[0,1] neg_hi:[0,1]
	s_nop 0
	v_pk_add_f32 v[4:5], v[4:5], v[34:35] neg_lo:[0,1] neg_hi:[0,1]
	s_nop 0
	v_pk_add_f32 v[2:3], v[2:3], v[4:5]
	v_pk_add_f32 v[4:5], v[50:51], v[16:17] neg_lo:[0,1] neg_hi:[0,1]
	s_nop 0
	v_pk_add_f32 v[2:3], v[4:5], v[2:3]
	v_pk_add_f32 v[4:5], v[22:23], v[48:49]
	v_pk_add_f32 v[2:3], v[52:53], v[2:3]
	v_pk_add_f32 v[16:17], v[4:5], v[22:23] neg_lo:[0,1] neg_hi:[0,1]
	v_pk_mul_f32 v[2:3], v[46:47], v[2:3]
	v_pk_add_f32 v[16:17], v[48:49], v[16:17] neg_lo:[0,1] neg_hi:[0,1]
	v_cvt_f32_i32_e32 v47, v56
	v_pk_add_f32 v[2:3], v[16:17], v[2:3]
	v_cvt_f32_i32_e32 v46, v45
	v_pk_add_f32 v[16:17], v[4:5], v[2:3]
	s_nop 0
	v_pk_mul_f32 v[22:23], v[16:17], v[16:17]
	v_pk_add_f32 v[4:5], v[16:17], v[4:5] neg_lo:[0,1] neg_hi:[0,1]
	v_pk_fma_f32 v[34:35], v[22:23], s[82:83], v[32:33] op_sel_hi:[1,0,0]
	v_pk_add_f32 v[2:3], v[2:3], v[4:5] neg_lo:[0,1] neg_hi:[0,1]
	v_ldexp_f32 v4, v16, 1
	v_pk_fma_f32 v[34:35], v[22:23], v[34:35], s[84:85] op_sel_hi:[1,1,0]
	v_ldexp_f32 v5, v17, 1
	v_pk_mul_f32 v[16:17], v[16:17], v[22:23]
	v_pk_mul_f32 v[22:23], v[46:47], s[86:87] op_sel_hi:[1,0]
	v_pk_mul_f32 v[16:17], v[16:17], v[34:35]
	v_pk_fma_f32 v[50:51], v[46:47], s[86:87], v[22:23] op_sel_hi:[1,0,1] neg_lo:[0,0,1] neg_hi:[0,0,1]
	v_pk_add_f32 v[34:35], v[4:5], v[16:17]
	v_ldexp_f32 v49, v3, 1
	v_pk_add_f32 v[4:5], v[34:35], v[4:5] neg_lo:[0,1] neg_hi:[0,1]
	v_pk_fma_f32 v[46:47], v[46:47], s[88:89], v[50:51] op_sel_hi:[1,0,1]
	v_pk_add_f32 v[4:5], v[16:17], v[4:5] neg_lo:[0,1] neg_hi:[0,1]
	v_ldexp_f32 v2, v2, 1
	v_mov_b32_e32 v16, v22
	v_mov_b32_e32 v17, v5
	v_mov_b32_e32 v48, v46
	v_mov_b32_e32 v3, v49
	v_pk_add_f32 v[16:17], v[16:17], v[48:49]
	v_pk_add_f32 v[48:49], v[2:3], v[4:5]
	v_mov_b32_e32 v5, v35
	v_mov_b32_e32 v3, v49
	v_pk_add_f32 v[50:51], v[22:23], v[46:47]
	v_pk_add_f32 v[2:3], v[2:3], v[4:5]
	v_pk_add_f32 v[4:5], v[34:35], v[48:49]
	v_mov_b32_e32 v60, v34
	v_pk_add_f32 v[52:53], v[50:51], v[4:5]
	v_mov_b32_e32 v58, v4
	v_mov_b32_e32 v59, v53
	v_mov_b32_e32 v61, v51
	v_pk_add_f32 v[58:59], v[58:59], v[60:61] neg_lo:[0,1] neg_hi:[0,1]
	v_mov_b32_e32 v54, v52
	v_mov_b32_e32 v55, v51
	v_mov_b32_e32 v56, v50
	v_mov_b32_e32 v57, v23
	v_mov_b32_e32 v60, v50
	v_mov_b32_e32 v61, v53
	v_mov_b32_e32 v23, v59
	v_pk_add_f32 v[54:55], v[54:55], v[56:57] neg_lo:[0,1] neg_hi:[0,1]
	v_mov_b32_e32 v56, v4
	v_mov_b32_e32 v57, v47
	v_pk_add_f32 v[22:23], v[60:61], v[22:23] neg_lo:[0,1] neg_hi:[0,1]
	v_pk_add_f32 v[56:57], v[56:57], v[54:55] neg_lo:[0,1] neg_hi:[0,1]
	v_mov_b32_e32 v60, v22
	v_mov_b32_e32 v61, v55
	v_mov_b32_e32 v62, v52
	v_mov_b32_e32 v63, v5
	v_mov_b32_e32 v55, v35
	v_pk_add_f32 v[60:61], v[46:47], v[60:61] neg_lo:[0,1] neg_hi:[0,1]
	v_pk_add_f32 v[54:55], v[62:63], v[54:55] neg_lo:[0,1] neg_hi:[0,1]
	v_mov_b32_e32 v47, v51
	v_pk_add_f32 v[16:17], v[16:17], v[54:55] neg_lo:[0,1] neg_hi:[0,1]
	v_pk_add_f32 v[22:23], v[46:47], v[22:23] neg_lo:[0,1] neg_hi:[0,1]
	v_pk_add_f32 v[2:3], v[2:3], v[58:59] neg_lo:[0,1] neg_hi:[0,1]
	v_pk_add_f32 v[4:5], v[4:5], v[34:35] neg_lo:[0,1] neg_hi:[0,1]
	v_pk_add_f32 v[34:35], v[2:3], v[22:23]
	v_mov_b32_e32 v23, v57
	v_mov_b32_e32 v3, v17
	v_pk_add_f32 v[46:47], v[56:57], v[16:17]
	v_pk_add_f32 v[2:3], v[22:23], v[2:3]
	v_mov_b32_e32 v16, v34
	v_pk_add_f32 v[2:3], v[2:3], v[60:61] neg_lo:[0,1] neg_hi:[0,1]
	v_mov_b32_e32 v17, v47
	v_pk_add_f32 v[4:5], v[48:49], v[4:5] neg_lo:[0,1] neg_hi:[0,1]
	v_pk_add_f32 v[16:17], v[16:17], v[2:3] neg_lo:[0,1] neg_hi:[0,1]
	v_pk_add_f32 v[2:3], v[4:5], v[2:3] neg_lo:[0,1] neg_hi:[0,1]
	v_pk_add_f32 v[16:17], v[22:23], v[16:17] neg_lo:[0,1] neg_hi:[0,1]
	v_pk_add_f32 v[4:5], v[46:47], v[34:35]
	v_pk_add_f32 v[2:3], v[2:3], v[16:17]
	v_pk_add_f32 v[16:17], v[52:53], v[4:5]
	s_nop 0
	v_pk_add_f32 v[22:23], v[16:17], v[52:53] neg_lo:[0,1] neg_hi:[0,1]
	s_nop 0
	v_pk_add_f32 v[4:5], v[4:5], v[22:23] neg_lo:[0,1] neg_hi:[0,1]
	s_nop 0
	v_pk_add_f32 v[2:3], v[2:3], v[4:5]
	v_fma_f32 v4, v6, v18, v31
	v_pk_add_f32 v[2:3], v[16:17], v[2:3]
	v_mul_f32_e64 v5, |v4|, s16
	v_cndmask_b32_e64 v2, v42, v2, s[10:11]
	v_cmp_neq_f32_e64 s[10:11], s18, v64
	v_exp_f32_e32 v45, v5
	s_nop 0
	v_cndmask_b32_e64 v3, v42, v3, s[10:11]
	v_cmp_ngt_f32_e64 s[10:11], -1.0, v64
	s_nop 1
	v_cndmask_b32_e64 v3, v43, v3, s[10:11]
	v_cmp_ngt_f32_e64 s[10:11], -1.0, v24
	s_nop 1
	v_cndmask_b32_e64 v2, v43, v2, s[10:11]
	v_cmp_neq_f32_e64 s[10:11], -1.0, v24
	s_nop 1
	v_cndmask_b32_e64 v2, v44, v2, s[10:11]
	v_cmp_neq_f32_e64 s[10:11], -1.0, v64
	s_nop 1
	v_cndmask_b32_e64 v3, v44, v3, s[10:11]
	v_cmp_lt_f32_e64 s[10:11], |v64|, s19
	s_nop 1
	v_cndmask_b32_e64 v3, v3, v64, s[10:11]
	v_cmp_lt_f32_e64 s[10:11], |v24|, s19
	s_nop 1
	v_cndmask_b32_e64 v2, v2, v24, s[10:11]
	v_pk_add_f32 v[0:1], v[0:1], v[2:3] neg_lo:[0,1] neg_hi:[0,1]
	v_add_f32_e32 v3, 1.0, v45
	v_min_f32_e32 v2, 0, v4
	v_add_f32_e32 v4, -1.0, v3
	v_sub_f32_e32 v5, v4, v3
	v_add_f32_e32 v5, 1.0, v5
	v_sub_f32_e32 v4, v45, v4
	v_add_f32_e32 v6, v4, v5
	v_frexp_mant_f32_e32 v16, v3
	v_cvt_f64_f32_e32 v[4:5], v3
	v_frexp_exp_i32_f64_e32 v4, v[4:5]
	v_cmp_gt_f32_e64 s[10:11], s17, v16
	s_nop 1
	v_subbrev_co_u32_e64 v24, s[10:11], 0, v4, s[10:11]
	v_mul_f32_e64 v4, |v7|, s16
	v_exp_f32_e32 v62, v4
	v_sub_u32_e32 v5, 0, v24
	v_ldexp_f32 v4, v3, v5
	v_ldexp_f32 v6, v6, v5
	v_add_f32_e32 v5, 1.0, v62
	v_min_f32_e32 v3, 0, v7
	v_add_f32_e32 v7, -1.0, v5
	v_sub_f32_e32 v16, v7, v5
	v_add_f32_e32 v16, 1.0, v16
	v_sub_f32_e32 v7, v62, v7
	v_add_f32_e32 v7, v7, v16
	v_frexp_mant_f32_e32 v18, v5
	v_cvt_f64_f32_e32 v[16:17], v5
	v_frexp_exp_i32_f64_e32 v16, v[16:17]
	v_cmp_gt_f32_e64 s[10:11], s17, v18
	s_nop 1
	v_subbrev_co_u32_e64 v54, s[10:11], 0, v16, s[10:11]
	v_sub_u32_e32 v16, 0, v54
	v_ldexp_f32 v5, v5, v16
	v_ldexp_f32 v7, v7, v16
	v_pk_add_f32 v[16:17], v[4:5], 1.0 op_sel_hi:[1,0]
	v_pk_add_f32 v[46:47], v[4:5], -1.0 op_sel_hi:[1,0]
	v_pk_add_f32 v[18:19], v[16:17], -1.0 op_sel_hi:[1,0]
	v_pk_add_f32 v[48:49], v[46:47], 1.0 op_sel_hi:[1,0]
	v_pk_add_f32 v[18:19], v[4:5], v[18:19] neg_lo:[0,1] neg_hi:[0,1]
	v_pk_add_f32 v[4:5], v[4:5], v[48:49] neg_lo:[0,1] neg_hi:[0,1]
	v_pk_add_f32 v[18:19], v[6:7], v[18:19]
	v_pk_add_f32 v[4:5], v[6:7], v[4:5]
	v_pk_add_f32 v[22:23], v[16:17], v[18:19]
	v_pk_add_f32 v[6:7], v[46:47], v[4:5]
	v_rcp_f32_e32 v34, v22
	v_rcp_f32_e32 v35, v23
	v_pk_add_f32 v[16:17], v[22:23], v[16:17] neg_lo:[0,1] neg_hi:[0,1]
	v_pk_add_f32 v[46:47], v[6:7], v[46:47] neg_lo:[0,1] neg_hi:[0,1]
	v_pk_add_f32 v[16:17], v[18:19], v[16:17] neg_lo:[0,1] neg_hi:[0,1]
	v_pk_mul_f32 v[18:19], v[6:7], v[34:35]
	v_pk_add_f32 v[4:5], v[4:5], v[46:47] neg_lo:[0,1] neg_hi:[0,1]
	v_pk_mul_f32 v[46:47], v[22:23], v[18:19]
	v_cmp_neq_f32_e64 s[10:11], s18, v45
	v_pk_fma_f32 v[48:49], v[18:19], v[22:23], v[46:47] neg_lo:[0,0,1] neg_hi:[0,0,1]
	s_nop 0
	v_pk_fma_f32 v[48:49], v[18:19], v[16:17], v[48:49]
	s_nop 0
	v_pk_add_f32 v[50:51], v[46:47], v[48:49]
	s_nop 0
	v_pk_add_f32 v[52:53], v[6:7], v[50:51] neg_lo:[0,1] neg_hi:[0,1]
	v_pk_add_f32 v[46:47], v[50:51], v[46:47] neg_lo:[0,1] neg_hi:[0,1]
	v_pk_add_f32 v[6:7], v[6:7], v[52:53] neg_lo:[0,1] neg_hi:[0,1]
	s_nop 0
	v_pk_add_f32 v[6:7], v[6:7], v[50:51] neg_lo:[0,1] neg_hi:[0,1]
	s_nop 0
	v_pk_add_f32 v[4:5], v[4:5], v[6:7]
	v_pk_add_f32 v[6:7], v[46:47], v[48:49] neg_lo:[0,1] neg_hi:[0,1]
	s_nop 0
	v_pk_add_f32 v[4:5], v[6:7], v[4:5]
	s_nop 0
	v_pk_add_f32 v[6:7], v[52:53], v[4:5]
	s_nop 0
	v_pk_mul_f32 v[46:47], v[34:35], v[6:7]
	s_nop 0
	v_pk_mul_f32 v[48:49], v[22:23], v[46:47]
	s_nop 0
	v_pk_fma_f32 v[22:23], v[46:47], v[22:23], v[48:49] neg_lo:[0,0,1] neg_hi:[0,0,1]
	s_nop 0
	v_pk_fma_f32 v[16:17], v[46:47], v[16:17], v[22:23]
	v_pk_add_f32 v[22:23], v[52:53], v[6:7] neg_lo:[0,1] neg_hi:[0,1]
	s_nop 0
	v_pk_add_f32 v[4:5], v[4:5], v[22:23]
	v_pk_add_f32 v[22:23], v[48:49], v[16:17]
	s_nop 0
	v_pk_add_f32 v[50:51], v[6:7], v[22:23] neg_lo:[0,1] neg_hi:[0,1]
	v_pk_add_f32 v[48:49], v[22:23], v[48:49] neg_lo:[0,1] neg_hi:[0,1]
	v_pk_add_f32 v[6:7], v[6:7], v[50:51] neg_lo:[0,1] neg_hi:[0,1]
	s_nop 0
	v_pk_add_f32 v[6:7], v[6:7], v[22:23] neg_lo:[0,1] neg_hi:[0,1]
	s_nop 0
	v_pk_add_f32 v[4:5], v[4:5], v[6:7]
	v_pk_add_f32 v[6:7], v[48:49], v[16:17] neg_lo:[0,1] neg_hi:[0,1]
	s_nop 0
	v_pk_add_f32 v[4:5], v[6:7], v[4:5]
	v_pk_add_f32 v[6:7], v[18:19], v[46:47]
	v_pk_add_f32 v[4:5], v[50:51], v[4:5]
	v_pk_add_f32 v[16:17], v[6:7], v[18:19] neg_lo:[0,1] neg_hi:[0,1]
	v_pk_mul_f32 v[4:5], v[34:35], v[4:5]
	v_pk_add_f32 v[16:17], v[46:47], v[16:17] neg_lo:[0,1] neg_hi:[0,1]
	v_cvt_f32_i32_e32 v35, v54
	v_pk_add_f32 v[4:5], v[16:17], v[4:5]
	v_cvt_f32_i32_e32 v34, v24
	v_pk_add_f32 v[16:17], v[6:7], v[4:5]
	s_nop 0
	v_pk_mul_f32 v[18:19], v[16:17], v[16:17]
	v_pk_add_f32 v[6:7], v[16:17], v[6:7] neg_lo:[0,1] neg_hi:[0,1]
	v_pk_fma_f32 v[22:23], v[18:19], s[82:83], v[32:33] op_sel_hi:[1,0,0]
	v_pk_add_f32 v[4:5], v[4:5], v[6:7] neg_lo:[0,1] neg_hi:[0,1]
	v_ldexp_f32 v6, v16, 1
	v_pk_fma_f32 v[22:23], v[18:19], v[22:23], s[84:85] op_sel_hi:[1,1,0]
	v_ldexp_f32 v7, v17, 1
	v_pk_mul_f32 v[16:17], v[16:17], v[18:19]
	v_pk_mul_f32 v[18:19], v[34:35], s[86:87] op_sel_hi:[1,0]
	v_pk_mul_f32 v[16:17], v[16:17], v[22:23]
	v_pk_fma_f32 v[48:49], v[34:35], s[86:87], v[18:19] op_sel_hi:[1,0,1] neg_lo:[0,0,1] neg_hi:[0,0,1]
	v_pk_add_f32 v[22:23], v[6:7], v[16:17]
	v_ldexp_f32 v47, v5, 1
	v_pk_add_f32 v[6:7], v[22:23], v[6:7] neg_lo:[0,1] neg_hi:[0,1]
	v_pk_fma_f32 v[34:35], v[34:35], s[88:89], v[48:49] op_sel_hi:[1,0,1]
	v_pk_add_f32 v[6:7], v[16:17], v[6:7] neg_lo:[0,1] neg_hi:[0,1]
	v_ldexp_f32 v4, v4, 1
	v_mov_b32_e32 v16, v18
	v_mov_b32_e32 v17, v7
	v_mov_b32_e32 v46, v34
	v_mov_b32_e32 v5, v47
	v_pk_add_f32 v[16:17], v[16:17], v[46:47]
	v_pk_add_f32 v[46:47], v[4:5], v[6:7]
	v_mov_b32_e32 v7, v23
	v_mov_b32_e32 v5, v47
	v_pk_add_f32 v[48:49], v[18:19], v[34:35]
	v_pk_add_f32 v[4:5], v[4:5], v[6:7]
	v_pk_add_f32 v[6:7], v[22:23], v[46:47]
	v_mov_b32_e32 v58, v22
	v_pk_add_f32 v[50:51], v[48:49], v[6:7]
	v_mov_b32_e32 v56, v6
	v_mov_b32_e32 v57, v51
	v_mov_b32_e32 v59, v49
	v_pk_add_f32 v[56:57], v[56:57], v[58:59] neg_lo:[0,1] neg_hi:[0,1]
	v_mov_b32_e32 v52, v50
	v_mov_b32_e32 v53, v49
	v_mov_b32_e32 v54, v48
	v_mov_b32_e32 v55, v19
	v_mov_b32_e32 v58, v48
	v_mov_b32_e32 v59, v51
	v_mov_b32_e32 v19, v57
	v_pk_add_f32 v[52:53], v[52:53], v[54:55] neg_lo:[0,1] neg_hi:[0,1]
	v_mov_b32_e32 v54, v6
	v_mov_b32_e32 v55, v35
	v_pk_add_f32 v[18:19], v[58:59], v[18:19] neg_lo:[0,1] neg_hi:[0,1]
	v_pk_add_f32 v[54:55], v[54:55], v[52:53] neg_lo:[0,1] neg_hi:[0,1]
	v_mov_b32_e32 v58, v18
	v_mov_b32_e32 v59, v53
	v_mov_b32_e32 v60, v50
	v_mov_b32_e32 v61, v7
	v_mov_b32_e32 v53, v23
	v_pk_add_f32 v[58:59], v[34:35], v[58:59] neg_lo:[0,1] neg_hi:[0,1]
	v_pk_add_f32 v[52:53], v[60:61], v[52:53] neg_lo:[0,1] neg_hi:[0,1]
	v_mov_b32_e32 v35, v49
	v_pk_add_f32 v[16:17], v[16:17], v[52:53] neg_lo:[0,1] neg_hi:[0,1]
	v_pk_add_f32 v[18:19], v[34:35], v[18:19] neg_lo:[0,1] neg_hi:[0,1]
	v_pk_add_f32 v[4:5], v[4:5], v[56:57] neg_lo:[0,1] neg_hi:[0,1]
	v_pk_add_f32 v[6:7], v[6:7], v[22:23] neg_lo:[0,1] neg_hi:[0,1]
	v_pk_add_f32 v[22:23], v[4:5], v[18:19]
	v_mov_b32_e32 v19, v55
	v_mov_b32_e32 v5, v17
	v_pk_add_f32 v[34:35], v[54:55], v[16:17]
	v_pk_add_f32 v[4:5], v[18:19], v[4:5]
	v_mov_b32_e32 v16, v22
	v_pk_add_f32 v[4:5], v[4:5], v[58:59] neg_lo:[0,1] neg_hi:[0,1]
	v_mov_b32_e32 v17, v35
	v_pk_add_f32 v[6:7], v[46:47], v[6:7] neg_lo:[0,1] neg_hi:[0,1]
	v_pk_add_f32 v[16:17], v[16:17], v[4:5] neg_lo:[0,1] neg_hi:[0,1]
	v_pk_add_f32 v[4:5], v[6:7], v[4:5] neg_lo:[0,1] neg_hi:[0,1]
	v_pk_add_f32 v[16:17], v[18:19], v[16:17] neg_lo:[0,1] neg_hi:[0,1]
	v_pk_add_f32 v[6:7], v[34:35], v[22:23]
	v_pk_add_f32 v[4:5], v[4:5], v[16:17]
	v_pk_add_f32 v[16:17], v[50:51], v[6:7]
	s_nop 0
	v_pk_add_f32 v[18:19], v[16:17], v[50:51] neg_lo:[0,1] neg_hi:[0,1]
	s_nop 0
	v_pk_add_f32 v[6:7], v[6:7], v[18:19] neg_lo:[0,1] neg_hi:[0,1]
	s_nop 0
	v_pk_add_f32 v[4:5], v[4:5], v[6:7]
	s_nop 0
	v_pk_add_f32 v[4:5], v[16:17], v[4:5]
	s_nop 0
	v_cndmask_b32_e64 v4, v42, v4, s[10:11]
	v_cmp_neq_f32_e64 s[10:11], s18, v62
	s_nop 1
	v_cndmask_b32_e64 v5, v42, v5, s[10:11]
	v_cmp_ngt_f32_e64 s[10:11], -1.0, v62
	s_nop 1
	v_cndmask_b32_e64 v5, v43, v5, s[10:11]
	v_cmp_ngt_f32_e64 s[10:11], -1.0, v45
	s_nop 1
	v_cndmask_b32_e64 v4, v43, v4, s[10:11]
	v_cmp_neq_f32_e64 s[10:11], -1.0, v45
	s_nop 1
	v_cndmask_b32_e64 v16, v44, v4, s[10:11]
	v_cmp_neq_f32_e64 s[10:11], -1.0, v62
	s_nop 1
	v_cndmask_b32_e64 v17, v44, v5, s[10:11]
	ds_read_b128 v[4:7], v40 offset:16576
	v_cmp_lt_f32_e64 s[10:11], |v62|, s19
	s_nop 1
	v_cndmask_b32_e64 v23, v17, v62, s[10:11]
	v_cmp_lt_f32_e64 s[10:11], |v45|, s19
	s_nop 1
	v_cndmask_b32_e64 v22, v16, v45, s[10:11]
	ds_read_b128 v[16:19], v40 offset:16608
	s_waitcnt lgkmcnt(1)
	v_fma_f32 v4, v8, v4, v31
	v_mul_f32_e64 v8, |v4|, s16
	v_exp_f32_e32 v24, v8
	v_pk_add_f32 v[2:3], v[2:3], v[22:23] neg_lo:[0,1] neg_hi:[0,1]
	global_store_dwordx4 v[20:21], v[0:3], off offset:32
	v_fma_f32 v5, v9, v5, v31
	v_fma_f32 v7, v11, v7, v31
	v_add_f32_e32 v1, 1.0, v24
	v_add_f32_e32 v2, -1.0, v1
	v_sub_f32_e32 v3, v2, v1
	v_add_f32_e32 v3, 1.0, v3
	v_sub_f32_e32 v2, v24, v2
	v_min_f32_e32 v0, 0, v4
	v_add_f32_e32 v4, v2, v3
	v_frexp_mant_f32_e32 v8, v1
	v_cvt_f64_f32_e32 v[2:3], v1
	v_frexp_exp_i32_f64_e32 v2, v[2:3]
	v_cmp_gt_f32_e64 s[10:11], s17, v8
	s_nop 1
	v_subbrev_co_u32_e64 v45, s[10:11], 0, v2, s[10:11]
	v_mul_f32_e64 v2, |v5|, s16
	v_exp_f32_e32 v64, v2
	v_sub_u32_e32 v3, 0, v45
	v_ldexp_f32 v2, v1, v3
	v_ldexp_f32 v4, v4, v3
	v_add_f32_e32 v3, 1.0, v64
	v_min_f32_e32 v1, 0, v5
	v_add_f32_e32 v5, -1.0, v3
	v_sub_f32_e32 v8, v5, v3
	v_add_f32_e32 v8, 1.0, v8
	v_sub_f32_e32 v5, v64, v5
	v_add_f32_e32 v5, v5, v8
	v_frexp_mant_f32_e32 v22, v3
	v_cvt_f64_f32_e32 v[8:9], v3
	v_frexp_exp_i32_f64_e32 v8, v[8:9]
	v_cmp_gt_f32_e64 s[10:11], s17, v22
	s_nop 1
	v_subbrev_co_u32_e64 v56, s[10:11], 0, v8, s[10:11]
	v_sub_u32_e32 v8, 0, v56
	v_ldexp_f32 v3, v3, v8
	v_ldexp_f32 v5, v5, v8
	v_pk_add_f32 v[8:9], v[2:3], 1.0 op_sel_hi:[1,0]
	v_pk_add_f32 v[48:49], v[2:3], -1.0 op_sel_hi:[1,0]
	v_pk_add_f32 v[22:23], v[8:9], -1.0 op_sel_hi:[1,0]
	v_pk_add_f32 v[50:51], v[48:49], 1.0 op_sel_hi:[1,0]
	v_pk_add_f32 v[22:23], v[2:3], v[22:23] neg_lo:[0,1] neg_hi:[0,1]
	v_pk_add_f32 v[2:3], v[2:3], v[50:51] neg_lo:[0,1] neg_hi:[0,1]
	v_pk_add_f32 v[22:23], v[4:5], v[22:23]
	v_pk_add_f32 v[2:3], v[4:5], v[2:3]
	v_pk_add_f32 v[34:35], v[8:9], v[22:23]
	v_pk_add_f32 v[4:5], v[48:49], v[2:3]
	v_rcp_f32_e32 v46, v34
	v_rcp_f32_e32 v47, v35
	v_pk_add_f32 v[8:9], v[34:35], v[8:9] neg_lo:[0,1] neg_hi:[0,1]
	v_pk_add_f32 v[48:49], v[4:5], v[48:49] neg_lo:[0,1] neg_hi:[0,1]
	v_pk_add_f32 v[8:9], v[22:23], v[8:9] neg_lo:[0,1] neg_hi:[0,1]
	v_pk_mul_f32 v[22:23], v[4:5], v[46:47]
	v_pk_add_f32 v[2:3], v[2:3], v[48:49] neg_lo:[0,1] neg_hi:[0,1]
	v_pk_mul_f32 v[48:49], v[34:35], v[22:23]
	v_cmp_neq_f32_e64 s[10:11], s18, v24
	v_pk_fma_f32 v[50:51], v[22:23], v[34:35], v[48:49] neg_lo:[0,0,1] neg_hi:[0,0,1]
	s_nop 0
	v_pk_fma_f32 v[50:51], v[22:23], v[8:9], v[50:51]
	s_nop 0
	v_pk_add_f32 v[52:53], v[48:49], v[50:51]
	s_nop 0
	v_pk_add_f32 v[54:55], v[4:5], v[52:53] neg_lo:[0,1] neg_hi:[0,1]
	v_pk_add_f32 v[48:49], v[52:53], v[48:49] neg_lo:[0,1] neg_hi:[0,1]
	v_pk_add_f32 v[4:5], v[4:5], v[54:55] neg_lo:[0,1] neg_hi:[0,1]
	s_nop 0
	v_pk_add_f32 v[4:5], v[4:5], v[52:53] neg_lo:[0,1] neg_hi:[0,1]
	s_nop 0
	v_pk_add_f32 v[2:3], v[2:3], v[4:5]
	v_pk_add_f32 v[4:5], v[48:49], v[50:51] neg_lo:[0,1] neg_hi:[0,1]
	s_nop 0
	v_pk_add_f32 v[2:3], v[4:5], v[2:3]
	s_nop 0
	v_pk_add_f32 v[4:5], v[54:55], v[2:3]
	s_nop 0
	v_pk_mul_f32 v[48:49], v[46:47], v[4:5]
	s_nop 0
	v_pk_mul_f32 v[50:51], v[34:35], v[48:49]
	s_nop 0
	v_pk_fma_f32 v[34:35], v[48:49], v[34:35], v[50:51] neg_lo:[0,0,1] neg_hi:[0,0,1]
	s_nop 0
	v_pk_fma_f32 v[8:9], v[48:49], v[8:9], v[34:35]
	v_pk_add_f32 v[34:35], v[54:55], v[4:5] neg_lo:[0,1] neg_hi:[0,1]
	s_nop 0
	v_pk_add_f32 v[2:3], v[2:3], v[34:35]
	v_pk_add_f32 v[34:35], v[50:51], v[8:9]
	s_nop 0
	v_pk_add_f32 v[52:53], v[4:5], v[34:35] neg_lo:[0,1] neg_hi:[0,1]
	v_pk_add_f32 v[50:51], v[34:35], v[50:51] neg_lo:[0,1] neg_hi:[0,1]
	v_pk_add_f32 v[4:5], v[4:5], v[52:53] neg_lo:[0,1] neg_hi:[0,1]
	s_nop 0
	v_pk_add_f32 v[4:5], v[4:5], v[34:35] neg_lo:[0,1] neg_hi:[0,1]
	s_nop 0
	v_pk_add_f32 v[2:3], v[2:3], v[4:5]
	v_pk_add_f32 v[4:5], v[50:51], v[8:9] neg_lo:[0,1] neg_hi:[0,1]
	s_nop 0
	v_pk_add_f32 v[2:3], v[4:5], v[2:3]
	v_pk_add_f32 v[4:5], v[22:23], v[48:49]
	v_pk_add_f32 v[2:3], v[52:53], v[2:3]
	v_pk_add_f32 v[8:9], v[4:5], v[22:23] neg_lo:[0,1] neg_hi:[0,1]
	v_pk_mul_f32 v[2:3], v[46:47], v[2:3]
	v_pk_add_f32 v[8:9], v[48:49], v[8:9] neg_lo:[0,1] neg_hi:[0,1]
	v_cvt_f32_i32_e32 v47, v56
	v_pk_add_f32 v[2:3], v[8:9], v[2:3]
	v_cvt_f32_i32_e32 v46, v45
	v_pk_add_f32 v[8:9], v[4:5], v[2:3]
	s_nop 0
	v_pk_mul_f32 v[22:23], v[8:9], v[8:9]
	v_pk_add_f32 v[4:5], v[8:9], v[4:5] neg_lo:[0,1] neg_hi:[0,1]
	v_pk_fma_f32 v[34:35], v[22:23], s[82:83], v[32:33] op_sel_hi:[1,0,0]
	v_pk_add_f32 v[2:3], v[2:3], v[4:5] neg_lo:[0,1] neg_hi:[0,1]
	v_ldexp_f32 v4, v8, 1
	v_pk_fma_f32 v[34:35], v[22:23], v[34:35], s[84:85] op_sel_hi:[1,1,0]
	v_ldexp_f32 v5, v9, 1
	v_pk_mul_f32 v[8:9], v[8:9], v[22:23]
	v_pk_mul_f32 v[22:23], v[46:47], s[86:87] op_sel_hi:[1,0]
	v_pk_mul_f32 v[8:9], v[8:9], v[34:35]
	v_pk_fma_f32 v[50:51], v[46:47], s[86:87], v[22:23] op_sel_hi:[1,0,1] neg_lo:[0,0,1] neg_hi:[0,0,1]
	v_pk_add_f32 v[34:35], v[4:5], v[8:9]
	v_ldexp_f32 v49, v3, 1
	v_pk_add_f32 v[4:5], v[34:35], v[4:5] neg_lo:[0,1] neg_hi:[0,1]
	v_pk_fma_f32 v[46:47], v[46:47], s[88:89], v[50:51] op_sel_hi:[1,0,1]
	v_pk_add_f32 v[4:5], v[8:9], v[4:5] neg_lo:[0,1] neg_hi:[0,1]
	v_ldexp_f32 v2, v2, 1
	v_mov_b32_e32 v8, v22
	v_mov_b32_e32 v9, v5
	v_mov_b32_e32 v48, v46
	v_mov_b32_e32 v3, v49
	v_pk_add_f32 v[8:9], v[8:9], v[48:49]
	v_pk_add_f32 v[48:49], v[2:3], v[4:5]
	v_mov_b32_e32 v5, v35
	v_mov_b32_e32 v3, v49
	v_pk_add_f32 v[50:51], v[22:23], v[46:47]
	v_pk_add_f32 v[2:3], v[2:3], v[4:5]
	v_pk_add_f32 v[4:5], v[34:35], v[48:49]
	v_mov_b32_e32 v60, v34
	v_pk_add_f32 v[52:53], v[50:51], v[4:5]
	v_mov_b32_e32 v58, v4
	v_mov_b32_e32 v59, v53
	v_mov_b32_e32 v61, v51
	v_pk_add_f32 v[58:59], v[58:59], v[60:61] neg_lo:[0,1] neg_hi:[0,1]
	v_mov_b32_e32 v54, v52
	v_mov_b32_e32 v55, v51
	v_mov_b32_e32 v56, v50
	v_mov_b32_e32 v57, v23
	v_mov_b32_e32 v60, v50
	v_mov_b32_e32 v61, v53
	v_mov_b32_e32 v23, v59
	v_pk_add_f32 v[54:55], v[54:55], v[56:57] neg_lo:[0,1] neg_hi:[0,1]
	v_mov_b32_e32 v56, v4
	v_mov_b32_e32 v57, v47
	v_pk_add_f32 v[22:23], v[60:61], v[22:23] neg_lo:[0,1] neg_hi:[0,1]
	v_pk_add_f32 v[56:57], v[56:57], v[54:55] neg_lo:[0,1] neg_hi:[0,1]
	v_mov_b32_e32 v60, v22
	v_mov_b32_e32 v61, v55
	v_mov_b32_e32 v62, v52
	v_mov_b32_e32 v63, v5
	v_mov_b32_e32 v55, v35
	v_pk_add_f32 v[60:61], v[46:47], v[60:61] neg_lo:[0,1] neg_hi:[0,1]
	v_pk_add_f32 v[54:55], v[62:63], v[54:55] neg_lo:[0,1] neg_hi:[0,1]
	v_mov_b32_e32 v47, v51
	v_pk_add_f32 v[8:9], v[8:9], v[54:55] neg_lo:[0,1] neg_hi:[0,1]
	v_pk_add_f32 v[22:23], v[46:47], v[22:23] neg_lo:[0,1] neg_hi:[0,1]
	v_pk_add_f32 v[2:3], v[2:3], v[58:59] neg_lo:[0,1] neg_hi:[0,1]
	v_pk_add_f32 v[4:5], v[4:5], v[34:35] neg_lo:[0,1] neg_hi:[0,1]
	v_pk_add_f32 v[34:35], v[2:3], v[22:23]
	v_mov_b32_e32 v23, v57
	v_mov_b32_e32 v3, v9
	v_pk_add_f32 v[46:47], v[56:57], v[8:9]
	v_pk_add_f32 v[2:3], v[22:23], v[2:3]
	v_mov_b32_e32 v8, v34
	v_pk_add_f32 v[2:3], v[2:3], v[60:61] neg_lo:[0,1] neg_hi:[0,1]
	v_mov_b32_e32 v9, v47
	v_pk_add_f32 v[4:5], v[48:49], v[4:5] neg_lo:[0,1] neg_hi:[0,1]
	v_pk_add_f32 v[8:9], v[8:9], v[2:3] neg_lo:[0,1] neg_hi:[0,1]
	v_pk_add_f32 v[2:3], v[4:5], v[2:3] neg_lo:[0,1] neg_hi:[0,1]
	v_pk_add_f32 v[8:9], v[22:23], v[8:9] neg_lo:[0,1] neg_hi:[0,1]
	v_pk_add_f32 v[4:5], v[46:47], v[34:35]
	v_pk_add_f32 v[2:3], v[2:3], v[8:9]
	v_pk_add_f32 v[8:9], v[52:53], v[4:5]
	s_nop 0
	v_pk_add_f32 v[22:23], v[8:9], v[52:53] neg_lo:[0,1] neg_hi:[0,1]
	s_nop 0
	v_pk_add_f32 v[4:5], v[4:5], v[22:23] neg_lo:[0,1] neg_hi:[0,1]
	s_nop 0
	v_pk_add_f32 v[2:3], v[2:3], v[4:5]
	v_fma_f32 v4, v10, v6, v31
	v_pk_add_f32 v[2:3], v[8:9], v[2:3]
	v_mul_f32_e64 v5, |v4|, s16
	v_cndmask_b32_e64 v2, v42, v2, s[10:11]
	v_cmp_neq_f32_e64 s[10:11], s18, v64
	v_exp_f32_e32 v45, v5
	s_nop 0
	v_cndmask_b32_e64 v3, v42, v3, s[10:11]
	v_cmp_ngt_f32_e64 s[10:11], -1.0, v64
	s_nop 1
	v_cndmask_b32_e64 v3, v43, v3, s[10:11]
	v_cmp_ngt_f32_e64 s[10:11], -1.0, v24
	s_nop 1
	v_cndmask_b32_e64 v2, v43, v2, s[10:11]
	v_cmp_neq_f32_e64 s[10:11], -1.0, v24
	s_nop 1
	v_cndmask_b32_e64 v2, v44, v2, s[10:11]
	v_cmp_neq_f32_e64 s[10:11], -1.0, v64
	s_nop 1
	v_cndmask_b32_e64 v3, v44, v3, s[10:11]
	v_cmp_lt_f32_e64 s[10:11], |v64|, s19
	s_nop 1
	v_cndmask_b32_e64 v3, v3, v64, s[10:11]
	v_cmp_lt_f32_e64 s[10:11], |v24|, s19
	s_nop 1
	v_cndmask_b32_e64 v2, v2, v24, s[10:11]
	v_pk_add_f32 v[0:1], v[0:1], v[2:3] neg_lo:[0,1] neg_hi:[0,1]
	v_add_f32_e32 v3, 1.0, v45
	v_min_f32_e32 v2, 0, v4
	v_add_f32_e32 v4, -1.0, v3
	v_sub_f32_e32 v5, v4, v3
	v_add_f32_e32 v5, 1.0, v5
	v_sub_f32_e32 v4, v45, v4
	v_add_f32_e32 v6, v4, v5
	v_frexp_mant_f32_e32 v8, v3
	v_cvt_f64_f32_e32 v[4:5], v3
	v_frexp_exp_i32_f64_e32 v4, v[4:5]
	v_cmp_gt_f32_e64 s[10:11], s17, v8
	s_nop 1
	v_subbrev_co_u32_e64 v24, s[10:11], 0, v4, s[10:11]
	v_mul_f32_e64 v4, |v7|, s16
	v_exp_f32_e32 v62, v4
	v_sub_u32_e32 v5, 0, v24
	v_ldexp_f32 v4, v3, v5
	v_ldexp_f32 v6, v6, v5
	v_add_f32_e32 v5, 1.0, v62
	v_min_f32_e32 v3, 0, v7
	v_add_f32_e32 v7, -1.0, v5
	v_sub_f32_e32 v8, v7, v5
	v_add_f32_e32 v8, 1.0, v8
	v_sub_f32_e32 v7, v62, v7
	v_add_f32_e32 v7, v7, v8
	v_frexp_mant_f32_e32 v10, v5
	v_cvt_f64_f32_e32 v[8:9], v5
	v_frexp_exp_i32_f64_e32 v8, v[8:9]
	v_cmp_gt_f32_e64 s[10:11], s17, v10
	s_nop 1
	v_subbrev_co_u32_e64 v54, s[10:11], 0, v8, s[10:11]
	v_sub_u32_e32 v8, 0, v54
	v_ldexp_f32 v5, v5, v8
	v_ldexp_f32 v7, v7, v8
	v_pk_add_f32 v[8:9], v[4:5], 1.0 op_sel_hi:[1,0]
	v_pk_add_f32 v[46:47], v[4:5], -1.0 op_sel_hi:[1,0]
	v_pk_add_f32 v[10:11], v[8:9], -1.0 op_sel_hi:[1,0]
	v_pk_add_f32 v[48:49], v[46:47], 1.0 op_sel_hi:[1,0]
	v_pk_add_f32 v[10:11], v[4:5], v[10:11] neg_lo:[0,1] neg_hi:[0,1]
	v_pk_add_f32 v[4:5], v[4:5], v[48:49] neg_lo:[0,1] neg_hi:[0,1]
	v_pk_add_f32 v[10:11], v[6:7], v[10:11]
	v_pk_add_f32 v[4:5], v[6:7], v[4:5]
	v_pk_add_f32 v[22:23], v[8:9], v[10:11]
	v_pk_add_f32 v[6:7], v[46:47], v[4:5]
	v_rcp_f32_e32 v34, v22
	v_rcp_f32_e32 v35, v23
	v_pk_add_f32 v[8:9], v[22:23], v[8:9] neg_lo:[0,1] neg_hi:[0,1]
	v_pk_add_f32 v[46:47], v[6:7], v[46:47] neg_lo:[0,1] neg_hi:[0,1]
	v_pk_add_f32 v[8:9], v[10:11], v[8:9] neg_lo:[0,1] neg_hi:[0,1]
	v_pk_mul_f32 v[10:11], v[6:7], v[34:35]
	v_pk_add_f32 v[4:5], v[4:5], v[46:47] neg_lo:[0,1] neg_hi:[0,1]
	v_pk_mul_f32 v[46:47], v[22:23], v[10:11]
	v_cmp_neq_f32_e64 s[10:11], s18, v45
	v_pk_fma_f32 v[48:49], v[10:11], v[22:23], v[46:47] neg_lo:[0,0,1] neg_hi:[0,0,1]
	s_nop 0
	v_pk_fma_f32 v[48:49], v[10:11], v[8:9], v[48:49]
	s_nop 0
	v_pk_add_f32 v[50:51], v[46:47], v[48:49]
	s_nop 0
	v_pk_add_f32 v[52:53], v[6:7], v[50:51] neg_lo:[0,1] neg_hi:[0,1]
	v_pk_add_f32 v[46:47], v[50:51], v[46:47] neg_lo:[0,1] neg_hi:[0,1]
	v_pk_add_f32 v[6:7], v[6:7], v[52:53] neg_lo:[0,1] neg_hi:[0,1]
	s_nop 0
	v_pk_add_f32 v[6:7], v[6:7], v[50:51] neg_lo:[0,1] neg_hi:[0,1]
	s_nop 0
	v_pk_add_f32 v[4:5], v[4:5], v[6:7]
	v_pk_add_f32 v[6:7], v[46:47], v[48:49] neg_lo:[0,1] neg_hi:[0,1]
	s_nop 0
	v_pk_add_f32 v[4:5], v[6:7], v[4:5]
	s_nop 0
	v_pk_add_f32 v[6:7], v[52:53], v[4:5]
	s_nop 0
	v_pk_mul_f32 v[46:47], v[34:35], v[6:7]
	s_nop 0
	v_pk_mul_f32 v[48:49], v[22:23], v[46:47]
	s_nop 0
	v_pk_fma_f32 v[22:23], v[46:47], v[22:23], v[48:49] neg_lo:[0,0,1] neg_hi:[0,0,1]
	s_nop 0
	v_pk_fma_f32 v[8:9], v[46:47], v[8:9], v[22:23]
	v_pk_add_f32 v[22:23], v[52:53], v[6:7] neg_lo:[0,1] neg_hi:[0,1]
	s_nop 0
	v_pk_add_f32 v[4:5], v[4:5], v[22:23]
	v_pk_add_f32 v[22:23], v[48:49], v[8:9]
	s_nop 0
	v_pk_add_f32 v[50:51], v[6:7], v[22:23] neg_lo:[0,1] neg_hi:[0,1]
	v_pk_add_f32 v[48:49], v[22:23], v[48:49] neg_lo:[0,1] neg_hi:[0,1]
	v_pk_add_f32 v[6:7], v[6:7], v[50:51] neg_lo:[0,1] neg_hi:[0,1]
	s_nop 0
	v_pk_add_f32 v[6:7], v[6:7], v[22:23] neg_lo:[0,1] neg_hi:[0,1]
	s_nop 0
	v_pk_add_f32 v[4:5], v[4:5], v[6:7]
	v_pk_add_f32 v[6:7], v[48:49], v[8:9] neg_lo:[0,1] neg_hi:[0,1]
	s_nop 0
	v_pk_add_f32 v[4:5], v[6:7], v[4:5]
	v_pk_add_f32 v[6:7], v[10:11], v[46:47]
	v_pk_add_f32 v[4:5], v[50:51], v[4:5]
	v_pk_add_f32 v[8:9], v[6:7], v[10:11] neg_lo:[0,1] neg_hi:[0,1]
	v_pk_mul_f32 v[4:5], v[34:35], v[4:5]
	v_pk_add_f32 v[8:9], v[46:47], v[8:9] neg_lo:[0,1] neg_hi:[0,1]
	v_cvt_f32_i32_e32 v35, v54
	v_pk_add_f32 v[4:5], v[8:9], v[4:5]
	v_cvt_f32_i32_e32 v34, v24
	v_pk_add_f32 v[8:9], v[6:7], v[4:5]
	s_nop 0
	v_pk_mul_f32 v[10:11], v[8:9], v[8:9]
	v_pk_add_f32 v[6:7], v[8:9], v[6:7] neg_lo:[0,1] neg_hi:[0,1]
	v_pk_fma_f32 v[22:23], v[10:11], s[82:83], v[32:33] op_sel_hi:[1,0,0]
	v_pk_add_f32 v[4:5], v[4:5], v[6:7] neg_lo:[0,1] neg_hi:[0,1]
	v_ldexp_f32 v6, v8, 1
	v_pk_fma_f32 v[22:23], v[10:11], v[22:23], s[84:85] op_sel_hi:[1,1,0]
	v_ldexp_f32 v7, v9, 1
	v_pk_mul_f32 v[8:9], v[8:9], v[10:11]
	v_pk_mul_f32 v[10:11], v[34:35], s[86:87] op_sel_hi:[1,0]
	v_pk_mul_f32 v[8:9], v[8:9], v[22:23]
	v_pk_fma_f32 v[48:49], v[34:35], s[86:87], v[10:11] op_sel_hi:[1,0,1] neg_lo:[0,0,1] neg_hi:[0,0,1]
	v_pk_add_f32 v[22:23], v[6:7], v[8:9]
	v_ldexp_f32 v47, v5, 1
	v_pk_add_f32 v[6:7], v[22:23], v[6:7] neg_lo:[0,1] neg_hi:[0,1]
	v_pk_fma_f32 v[34:35], v[34:35], s[88:89], v[48:49] op_sel_hi:[1,0,1]
	v_pk_add_f32 v[6:7], v[8:9], v[6:7] neg_lo:[0,1] neg_hi:[0,1]
	v_ldexp_f32 v4, v4, 1
	v_mov_b32_e32 v8, v10
	v_mov_b32_e32 v9, v7
	v_mov_b32_e32 v46, v34
	v_mov_b32_e32 v5, v47
	v_pk_add_f32 v[8:9], v[8:9], v[46:47]
	v_pk_add_f32 v[46:47], v[4:5], v[6:7]
	v_mov_b32_e32 v7, v23
	v_mov_b32_e32 v5, v47
	v_pk_add_f32 v[48:49], v[10:11], v[34:35]
	v_pk_add_f32 v[4:5], v[4:5], v[6:7]
	v_pk_add_f32 v[6:7], v[22:23], v[46:47]
	v_mov_b32_e32 v58, v22
	v_pk_add_f32 v[50:51], v[48:49], v[6:7]
	v_mov_b32_e32 v56, v6
	v_mov_b32_e32 v57, v51
	v_mov_b32_e32 v59, v49
	v_pk_add_f32 v[56:57], v[56:57], v[58:59] neg_lo:[0,1] neg_hi:[0,1]
	v_mov_b32_e32 v52, v50
	v_mov_b32_e32 v53, v49
	v_mov_b32_e32 v54, v48
	v_mov_b32_e32 v55, v11
	v_mov_b32_e32 v58, v48
	v_mov_b32_e32 v59, v51
	v_mov_b32_e32 v11, v57
	v_pk_add_f32 v[52:53], v[52:53], v[54:55] neg_lo:[0,1] neg_hi:[0,1]
	v_mov_b32_e32 v54, v6
	v_mov_b32_e32 v55, v35
	v_pk_add_f32 v[10:11], v[58:59], v[10:11] neg_lo:[0,1] neg_hi:[0,1]
	v_pk_add_f32 v[54:55], v[54:55], v[52:53] neg_lo:[0,1] neg_hi:[0,1]
	v_mov_b32_e32 v58, v10
	v_mov_b32_e32 v59, v53
	v_mov_b32_e32 v60, v50
	v_mov_b32_e32 v61, v7
	v_mov_b32_e32 v53, v23
	v_pk_add_f32 v[58:59], v[34:35], v[58:59] neg_lo:[0,1] neg_hi:[0,1]
	v_pk_add_f32 v[52:53], v[60:61], v[52:53] neg_lo:[0,1] neg_hi:[0,1]
	v_mov_b32_e32 v35, v49
	v_pk_add_f32 v[8:9], v[8:9], v[52:53] neg_lo:[0,1] neg_hi:[0,1]
	v_pk_add_f32 v[10:11], v[34:35], v[10:11] neg_lo:[0,1] neg_hi:[0,1]
	v_pk_add_f32 v[4:5], v[4:5], v[56:57] neg_lo:[0,1] neg_hi:[0,1]
	v_pk_add_f32 v[6:7], v[6:7], v[22:23] neg_lo:[0,1] neg_hi:[0,1]
	v_pk_add_f32 v[22:23], v[4:5], v[10:11]
	v_mov_b32_e32 v11, v55
	v_mov_b32_e32 v5, v9
	v_pk_add_f32 v[34:35], v[54:55], v[8:9]
	v_pk_add_f32 v[4:5], v[10:11], v[4:5]
	v_mov_b32_e32 v8, v22
	v_pk_add_f32 v[4:5], v[4:5], v[58:59] neg_lo:[0,1] neg_hi:[0,1]
	v_mov_b32_e32 v9, v35
	v_pk_add_f32 v[6:7], v[46:47], v[6:7] neg_lo:[0,1] neg_hi:[0,1]
	v_pk_add_f32 v[8:9], v[8:9], v[4:5] neg_lo:[0,1] neg_hi:[0,1]
	v_pk_add_f32 v[4:5], v[6:7], v[4:5] neg_lo:[0,1] neg_hi:[0,1]
	v_pk_add_f32 v[8:9], v[10:11], v[8:9] neg_lo:[0,1] neg_hi:[0,1]
	v_pk_add_f32 v[6:7], v[34:35], v[22:23]
	v_pk_add_f32 v[4:5], v[4:5], v[8:9]
	v_pk_add_f32 v[8:9], v[50:51], v[6:7]
	s_nop 0
	v_pk_add_f32 v[10:11], v[8:9], v[50:51] neg_lo:[0,1] neg_hi:[0,1]
	s_nop 0
	v_pk_add_f32 v[6:7], v[6:7], v[10:11] neg_lo:[0,1] neg_hi:[0,1]
	s_nop 0
	v_pk_add_f32 v[4:5], v[4:5], v[6:7]
	s_waitcnt lgkmcnt(0)
	v_fma_f32 v6, v12, v16, v31
	v_pk_add_f32 v[4:5], v[8:9], v[4:5]
	v_mul_f32_e64 v7, |v6|, s16
	v_cndmask_b32_e64 v4, v42, v4, s[10:11]
	v_cmp_neq_f32_e64 s[10:11], s18, v62
	v_exp_f32_e32 v24, v7
	s_nop 0
	v_cndmask_b32_e64 v5, v42, v5, s[10:11]
	v_cmp_ngt_f32_e64 s[10:11], -1.0, v62
	s_nop 1
	v_cndmask_b32_e64 v5, v43, v5, s[10:11]
	v_cmp_ngt_f32_e64 s[10:11], -1.0, v45
	s_nop 1
	v_cndmask_b32_e64 v4, v43, v4, s[10:11]
	v_cmp_neq_f32_e64 s[10:11], -1.0, v45
	s_nop 1
	v_cndmask_b32_e64 v4, v44, v4, s[10:11]
	v_cmp_neq_f32_e64 s[10:11], -1.0, v62
	s_nop 1
	v_cndmask_b32_e64 v5, v44, v5, s[10:11]
	v_cmp_lt_f32_e64 s[10:11], |v62|, s19
	s_nop 1
	v_cndmask_b32_e64 v5, v5, v62, s[10:11]
	v_cmp_lt_f32_e64 s[10:11], |v45|, s19
	s_nop 1
	v_cndmask_b32_e64 v4, v4, v45, s[10:11]
	v_pk_add_f32 v[2:3], v[2:3], v[4:5] neg_lo:[0,1] neg_hi:[0,1]
	global_store_dwordx4 v[20:21], v[0:3], off offset:64
	s_nop 1
	v_add_f32_e32 v1, 1.0, v24
	v_add_f32_e32 v2, -1.0, v1
	v_sub_f32_e32 v3, v2, v1
	v_add_f32_e32 v3, 1.0, v3
	v_sub_f32_e32 v2, v24, v2
	v_add_f32_e32 v4, v2, v3
	v_frexp_mant_f32_e32 v5, v1
	v_cvt_f64_f32_e32 v[2:3], v1
	v_frexp_exp_i32_f64_e32 v2, v[2:3]
	v_cmp_gt_f32_e64 s[10:11], s17, v5
	v_fma_f32 v5, v13, v17, v31
	v_min_f32_e32 v0, 0, v6
	v_subbrev_co_u32_e64 v45, s[10:11], 0, v2, s[10:11]
	v_mul_f32_e64 v2, |v5|, s16
	v_exp_f32_e32 v56, v2
	v_sub_u32_e32 v3, 0, v45
	v_ldexp_f32 v2, v1, v3
	v_ldexp_f32 v4, v4, v3
	v_add_f32_e32 v3, 1.0, v56
	v_min_f32_e32 v1, 0, v5
	v_add_f32_e32 v5, -1.0, v3
	v_sub_f32_e32 v6, v5, v3
	v_add_f32_e32 v6, 1.0, v6
	v_sub_f32_e32 v5, v56, v5
	v_add_f32_e32 v5, v5, v6
	v_frexp_mant_f32_e32 v8, v3
	v_cvt_f64_f32_e32 v[6:7], v3
	v_frexp_exp_i32_f64_e32 v6, v[6:7]
	v_cmp_gt_f32_e64 s[10:11], s17, v8
	s_nop 1
	v_subbrev_co_u32_e64 v48, s[10:11], 0, v6, s[10:11]
	v_sub_u32_e32 v6, 0, v48
	v_ldexp_f32 v3, v3, v6
	v_ldexp_f32 v5, v5, v6
	v_pk_add_f32 v[6:7], v[2:3], 1.0 op_sel_hi:[1,0]
	v_pk_add_f32 v[16:17], v[2:3], -1.0 op_sel_hi:[1,0]
	v_pk_add_f32 v[8:9], v[6:7], -1.0 op_sel_hi:[1,0]
	v_pk_add_f32 v[22:23], v[16:17], 1.0 op_sel_hi:[1,0]
	v_pk_add_f32 v[8:9], v[2:3], v[8:9] neg_lo:[0,1] neg_hi:[0,1]
	v_pk_add_f32 v[2:3], v[2:3], v[22:23] neg_lo:[0,1] neg_hi:[0,1]
	v_pk_add_f32 v[8:9], v[4:5], v[8:9]
	v_pk_add_f32 v[2:3], v[4:5], v[2:3]
	v_pk_add_f32 v[10:11], v[6:7], v[8:9]
	v_pk_add_f32 v[4:5], v[16:17], v[2:3]
	v_rcp_f32_e32 v12, v10
	v_rcp_f32_e32 v13, v11
	v_pk_add_f32 v[6:7], v[10:11], v[6:7] neg_lo:[0,1] neg_hi:[0,1]
	v_pk_add_f32 v[16:17], v[4:5], v[16:17] neg_lo:[0,1] neg_hi:[0,1]
	v_pk_add_f32 v[6:7], v[8:9], v[6:7] neg_lo:[0,1] neg_hi:[0,1]
	v_pk_mul_f32 v[8:9], v[4:5], v[12:13]
	v_pk_add_f32 v[2:3], v[2:3], v[16:17] neg_lo:[0,1] neg_hi:[0,1]
	v_pk_mul_f32 v[16:17], v[10:11], v[8:9]
	v_cmp_neq_f32_e64 s[10:11], s18, v24
	v_pk_fma_f32 v[22:23], v[8:9], v[10:11], v[16:17] neg_lo:[0,0,1] neg_hi:[0,0,1]
	s_nop 0
	v_pk_fma_f32 v[22:23], v[8:9], v[6:7], v[22:23]
	s_nop 0
	v_pk_add_f32 v[34:35], v[16:17], v[22:23]
	s_nop 0
	v_pk_add_f32 v[46:47], v[4:5], v[34:35] neg_lo:[0,1] neg_hi:[0,1]
	v_pk_add_f32 v[16:17], v[34:35], v[16:17] neg_lo:[0,1] neg_hi:[0,1]
	v_pk_add_f32 v[4:5], v[4:5], v[46:47] neg_lo:[0,1] neg_hi:[0,1]
	s_nop 0
	v_pk_add_f32 v[4:5], v[4:5], v[34:35] neg_lo:[0,1] neg_hi:[0,1]
	s_nop 0
	v_pk_add_f32 v[2:3], v[2:3], v[4:5]
	v_pk_add_f32 v[4:5], v[16:17], v[22:23] neg_lo:[0,1] neg_hi:[0,1]
	s_nop 0
	v_pk_add_f32 v[2:3], v[4:5], v[2:3]
	s_nop 0
	v_pk_add_f32 v[4:5], v[46:47], v[2:3]
	s_nop 0
	v_pk_mul_f32 v[16:17], v[12:13], v[4:5]
	s_nop 0
	v_pk_mul_f32 v[22:23], v[10:11], v[16:17]
	s_nop 0
	v_pk_fma_f32 v[10:11], v[16:17], v[10:11], v[22:23] neg_lo:[0,0,1] neg_hi:[0,0,1]
	s_nop 0
	v_pk_fma_f32 v[6:7], v[16:17], v[6:7], v[10:11]
	v_pk_add_f32 v[10:11], v[46:47], v[4:5] neg_lo:[0,1] neg_hi:[0,1]
	s_nop 0
	v_pk_add_f32 v[2:3], v[2:3], v[10:11]
	v_pk_add_f32 v[10:11], v[22:23], v[6:7]
	s_nop 0
	v_pk_add_f32 v[34:35], v[4:5], v[10:11] neg_lo:[0,1] neg_hi:[0,1]
	v_pk_add_f32 v[22:23], v[10:11], v[22:23] neg_lo:[0,1] neg_hi:[0,1]
	v_pk_add_f32 v[4:5], v[4:5], v[34:35] neg_lo:[0,1] neg_hi:[0,1]
	s_nop 0
	v_pk_add_f32 v[4:5], v[4:5], v[10:11] neg_lo:[0,1] neg_hi:[0,1]
	s_nop 0
	v_pk_add_f32 v[2:3], v[2:3], v[4:5]
	v_pk_add_f32 v[4:5], v[22:23], v[6:7] neg_lo:[0,1] neg_hi:[0,1]
	s_nop 0
	v_pk_add_f32 v[2:3], v[4:5], v[2:3]
	v_pk_add_f32 v[4:5], v[8:9], v[16:17]
	v_pk_add_f32 v[2:3], v[34:35], v[2:3]
	v_pk_add_f32 v[6:7], v[4:5], v[8:9] neg_lo:[0,1] neg_hi:[0,1]
	v_pk_mul_f32 v[2:3], v[12:13], v[2:3]
	v_pk_add_f32 v[6:7], v[16:17], v[6:7] neg_lo:[0,1] neg_hi:[0,1]
	v_cvt_f32_i32_e32 v13, v48
	v_pk_add_f32 v[2:3], v[6:7], v[2:3]
	v_cvt_f32_i32_e32 v12, v45
	v_pk_add_f32 v[6:7], v[4:5], v[2:3]
	s_nop 0
	v_pk_mul_f32 v[8:9], v[6:7], v[6:7]
	v_pk_add_f32 v[4:5], v[6:7], v[4:5] neg_lo:[0,1] neg_hi:[0,1]
	v_pk_fma_f32 v[10:11], v[8:9], s[82:83], v[32:33] op_sel_hi:[1,0,0]
	v_pk_add_f32 v[2:3], v[2:3], v[4:5] neg_lo:[0,1] neg_hi:[0,1]
	v_ldexp_f32 v4, v6, 1
	v_pk_fma_f32 v[10:11], v[8:9], v[10:11], s[84:85] op_sel_hi:[1,1,0]
	v_ldexp_f32 v5, v7, 1
	v_pk_mul_f32 v[6:7], v[6:7], v[8:9]
	v_pk_mul_f32 v[8:9], v[12:13], s[86:87] op_sel_hi:[1,0]
	v_pk_mul_f32 v[6:7], v[6:7], v[10:11]
	v_pk_fma_f32 v[22:23], v[12:13], s[86:87], v[8:9] op_sel_hi:[1,0,1] neg_lo:[0,0,1] neg_hi:[0,0,1]
	v_pk_add_f32 v[10:11], v[4:5], v[6:7]
	v_ldexp_f32 v17, v3, 1
	v_pk_add_f32 v[4:5], v[10:11], v[4:5] neg_lo:[0,1] neg_hi:[0,1]
	v_pk_fma_f32 v[12:13], v[12:13], s[88:89], v[22:23] op_sel_hi:[1,0,1]
	v_pk_add_f32 v[4:5], v[6:7], v[4:5] neg_lo:[0,1] neg_hi:[0,1]
	v_ldexp_f32 v2, v2, 1
	v_mov_b32_e32 v6, v8
	v_mov_b32_e32 v7, v5
	v_mov_b32_e32 v16, v12
	v_mov_b32_e32 v3, v17
	v_pk_add_f32 v[6:7], v[6:7], v[16:17]
	v_pk_add_f32 v[16:17], v[2:3], v[4:5]
	v_mov_b32_e32 v5, v11
	v_mov_b32_e32 v3, v17
	v_pk_add_f32 v[22:23], v[8:9], v[12:13]
	v_pk_add_f32 v[2:3], v[2:3], v[4:5]
	v_pk_add_f32 v[4:5], v[10:11], v[16:17]
	v_mov_b32_e32 v52, v10
	v_pk_add_f32 v[34:35], v[22:23], v[4:5]
	v_mov_b32_e32 v50, v4
	v_mov_b32_e32 v51, v35
	v_mov_b32_e32 v53, v23
	v_pk_add_f32 v[50:51], v[50:51], v[52:53] neg_lo:[0,1] neg_hi:[0,1]
	v_mov_b32_e32 v46, v34
	v_mov_b32_e32 v47, v23
	v_mov_b32_e32 v48, v22
	v_mov_b32_e32 v49, v9
	v_mov_b32_e32 v52, v22
	v_mov_b32_e32 v53, v35
	v_mov_b32_e32 v9, v51
	v_pk_add_f32 v[46:47], v[46:47], v[48:49] neg_lo:[0,1] neg_hi:[0,1]
	v_mov_b32_e32 v48, v4
	v_mov_b32_e32 v49, v13
	v_pk_add_f32 v[8:9], v[52:53], v[8:9] neg_lo:[0,1] neg_hi:[0,1]
	v_pk_add_f32 v[48:49], v[48:49], v[46:47] neg_lo:[0,1] neg_hi:[0,1]
	v_mov_b32_e32 v52, v8
	v_mov_b32_e32 v53, v47
	v_mov_b32_e32 v54, v34
	v_mov_b32_e32 v55, v5
	v_mov_b32_e32 v47, v11
	v_pk_add_f32 v[52:53], v[12:13], v[52:53] neg_lo:[0,1] neg_hi:[0,1]
	v_pk_add_f32 v[46:47], v[54:55], v[46:47] neg_lo:[0,1] neg_hi:[0,1]
	v_mov_b32_e32 v13, v23
	v_pk_add_f32 v[6:7], v[6:7], v[46:47] neg_lo:[0,1] neg_hi:[0,1]
	v_pk_add_f32 v[8:9], v[12:13], v[8:9] neg_lo:[0,1] neg_hi:[0,1]
	v_pk_add_f32 v[2:3], v[2:3], v[50:51] neg_lo:[0,1] neg_hi:[0,1]
	v_pk_add_f32 v[4:5], v[4:5], v[10:11] neg_lo:[0,1] neg_hi:[0,1]
	v_pk_add_f32 v[10:11], v[2:3], v[8:9]
	v_mov_b32_e32 v9, v49
	v_mov_b32_e32 v3, v7
	v_pk_add_f32 v[12:13], v[48:49], v[6:7]
	v_pk_add_f32 v[2:3], v[8:9], v[2:3]
	v_mov_b32_e32 v6, v10
	v_pk_add_f32 v[2:3], v[2:3], v[52:53] neg_lo:[0,1] neg_hi:[0,1]
	v_mov_b32_e32 v7, v13
	v_pk_add_f32 v[4:5], v[16:17], v[4:5] neg_lo:[0,1] neg_hi:[0,1]
	v_pk_add_f32 v[6:7], v[6:7], v[2:3] neg_lo:[0,1] neg_hi:[0,1]
	v_pk_add_f32 v[2:3], v[4:5], v[2:3] neg_lo:[0,1] neg_hi:[0,1]
	v_pk_add_f32 v[6:7], v[8:9], v[6:7] neg_lo:[0,1] neg_hi:[0,1]
	v_pk_add_f32 v[4:5], v[12:13], v[10:11]
	v_pk_add_f32 v[2:3], v[2:3], v[6:7]
	v_pk_add_f32 v[6:7], v[34:35], v[4:5]
	s_nop 0
	v_pk_add_f32 v[8:9], v[6:7], v[34:35] neg_lo:[0,1] neg_hi:[0,1]
	s_nop 0
	v_pk_add_f32 v[4:5], v[4:5], v[8:9] neg_lo:[0,1] neg_hi:[0,1]
	s_nop 0
	v_pk_add_f32 v[2:3], v[2:3], v[4:5]
	v_fma_f32 v4, v14, v18, v31
	v_pk_add_f32 v[2:3], v[6:7], v[2:3]
	v_mul_f32_e64 v5, |v4|, s16
	v_cndmask_b32_e64 v2, v42, v2, s[10:11]
	v_cmp_neq_f32_e64 s[10:11], s18, v56
	v_exp_f32_e32 v45, v5
	v_fmac_f32_e32 v31, v15, v19
	v_cndmask_b32_e64 v3, v42, v3, s[10:11]
	v_cmp_ngt_f32_e64 s[10:11], -1.0, v56
	s_nop 1
	v_cndmask_b32_e64 v3, v43, v3, s[10:11]
	v_cmp_ngt_f32_e64 s[10:11], -1.0, v24
	s_nop 1
	v_cndmask_b32_e64 v2, v43, v2, s[10:11]
	v_cmp_neq_f32_e64 s[10:11], -1.0, v24
	s_nop 1
	v_cndmask_b32_e64 v2, v44, v2, s[10:11]
	v_cmp_neq_f32_e64 s[10:11], -1.0, v56
	s_nop 1
	v_cndmask_b32_e64 v3, v44, v3, s[10:11]
	v_cmp_lt_f32_e64 s[10:11], |v56|, s19
	s_nop 1
	v_cndmask_b32_e64 v3, v3, v56, s[10:11]
	v_cmp_lt_f32_e64 s[10:11], |v24|, s19
	s_nop 1
	v_cndmask_b32_e64 v2, v2, v24, s[10:11]
	v_pk_add_f32 v[0:1], v[0:1], v[2:3] neg_lo:[0,1] neg_hi:[0,1]
	v_add_f32_e32 v3, 1.0, v45
	v_min_f32_e32 v2, 0, v4
	v_add_f32_e32 v4, -1.0, v3
	v_sub_f32_e32 v5, v4, v3
	v_add_f32_e32 v5, 1.0, v5
	v_sub_f32_e32 v4, v45, v4
	v_add_f32_e32 v6, v4, v5
	v_frexp_mant_f32_e32 v7, v3
	v_cvt_f64_f32_e32 v[4:5], v3
	v_frexp_exp_i32_f64_e32 v4, v[4:5]
	v_cmp_gt_f32_e64 s[10:11], s17, v7
	s_nop 1
	v_subbrev_co_u32_e64 v24, s[10:11], 0, v4, s[10:11]
	v_mul_f32_e64 v4, |v31|, s16
	v_exp_f32_e32 v52, v4
	v_sub_u32_e32 v5, 0, v24
	v_ldexp_f32 v4, v3, v5
	v_ldexp_f32 v6, v6, v5
	v_add_f32_e32 v5, 1.0, v52
	v_add_f32_e32 v7, -1.0, v5
	v_sub_f32_e32 v8, v7, v5
	v_add_f32_e32 v8, 1.0, v8
	v_sub_f32_e32 v7, v52, v7
	v_add_f32_e32 v7, v7, v8
	v_frexp_mant_f32_e32 v10, v5
	v_cvt_f64_f32_e32 v[8:9], v5
	v_frexp_exp_i32_f64_e32 v8, v[8:9]
	v_cmp_gt_f32_e64 s[10:11], s17, v10
	v_min_f32_e32 v3, 0, v31
	s_nop 0
	v_subbrev_co_u32_e64 v31, s[10:11], 0, v8, s[10:11]
	v_sub_u32_e32 v8, 0, v31
	v_ldexp_f32 v5, v5, v8
	v_ldexp_f32 v7, v7, v8
	v_pk_add_f32 v[8:9], v[4:5], 1.0 op_sel_hi:[1,0]
	v_pk_add_f32 v[16:17], v[4:5], -1.0 op_sel_hi:[1,0]
	v_pk_add_f32 v[10:11], v[8:9], -1.0 op_sel_hi:[1,0]
	v_pk_add_f32 v[18:19], v[16:17], 1.0 op_sel_hi:[1,0]
	v_pk_add_f32 v[10:11], v[4:5], v[10:11] neg_lo:[0,1] neg_hi:[0,1]
	v_pk_add_f32 v[4:5], v[4:5], v[18:19] neg_lo:[0,1] neg_hi:[0,1]
	v_pk_add_f32 v[10:11], v[6:7], v[10:11]
	v_pk_add_f32 v[4:5], v[6:7], v[4:5]
	v_pk_add_f32 v[12:13], v[8:9], v[10:11]
	v_pk_add_f32 v[6:7], v[16:17], v[4:5]
	v_rcp_f32_e32 v14, v12
	v_rcp_f32_e32 v15, v13
	v_pk_add_f32 v[8:9], v[12:13], v[8:9] neg_lo:[0,1] neg_hi:[0,1]
	v_pk_add_f32 v[16:17], v[6:7], v[16:17] neg_lo:[0,1] neg_hi:[0,1]
	v_pk_add_f32 v[8:9], v[10:11], v[8:9] neg_lo:[0,1] neg_hi:[0,1]
	v_pk_mul_f32 v[10:11], v[6:7], v[14:15]
	v_pk_add_f32 v[4:5], v[4:5], v[16:17] neg_lo:[0,1] neg_hi:[0,1]
	v_pk_mul_f32 v[16:17], v[12:13], v[10:11]
	v_cmp_neq_f32_e64 s[10:11], s18, v45
	v_pk_fma_f32 v[18:19], v[10:11], v[12:13], v[16:17] neg_lo:[0,0,1] neg_hi:[0,0,1]
	s_nop 0
	v_pk_fma_f32 v[18:19], v[10:11], v[8:9], v[18:19]
	s_nop 0
	v_pk_add_f32 v[22:23], v[16:17], v[18:19]
	s_nop 0
	v_pk_add_f32 v[34:35], v[6:7], v[22:23] neg_lo:[0,1] neg_hi:[0,1]
	v_pk_add_f32 v[16:17], v[22:23], v[16:17] neg_lo:[0,1] neg_hi:[0,1]
	v_pk_add_f32 v[6:7], v[6:7], v[34:35] neg_lo:[0,1] neg_hi:[0,1]
	s_nop 0
	v_pk_add_f32 v[6:7], v[6:7], v[22:23] neg_lo:[0,1] neg_hi:[0,1]
	s_nop 0
	v_pk_add_f32 v[4:5], v[4:5], v[6:7]
	v_pk_add_f32 v[6:7], v[16:17], v[18:19] neg_lo:[0,1] neg_hi:[0,1]
	s_nop 0
	v_pk_add_f32 v[4:5], v[6:7], v[4:5]
	s_nop 0
	v_pk_add_f32 v[6:7], v[34:35], v[4:5]
	s_nop 0
	v_pk_mul_f32 v[16:17], v[14:15], v[6:7]
	s_nop 0
	v_pk_mul_f32 v[18:19], v[12:13], v[16:17]
	s_nop 0
	v_pk_fma_f32 v[12:13], v[16:17], v[12:13], v[18:19] neg_lo:[0,0,1] neg_hi:[0,0,1]
	s_nop 0
	v_pk_fma_f32 v[8:9], v[16:17], v[8:9], v[12:13]
	v_pk_add_f32 v[12:13], v[34:35], v[6:7] neg_lo:[0,1] neg_hi:[0,1]
	s_nop 0
	v_pk_add_f32 v[4:5], v[4:5], v[12:13]
	v_pk_add_f32 v[12:13], v[18:19], v[8:9]
	s_nop 0
	v_pk_add_f32 v[22:23], v[6:7], v[12:13] neg_lo:[0,1] neg_hi:[0,1]
	v_pk_add_f32 v[18:19], v[12:13], v[18:19] neg_lo:[0,1] neg_hi:[0,1]
	v_pk_add_f32 v[6:7], v[6:7], v[22:23] neg_lo:[0,1] neg_hi:[0,1]
	s_nop 0
	v_pk_add_f32 v[6:7], v[6:7], v[12:13] neg_lo:[0,1] neg_hi:[0,1]
	s_nop 0
	v_pk_add_f32 v[4:5], v[4:5], v[6:7]
	v_pk_add_f32 v[6:7], v[18:19], v[8:9] neg_lo:[0,1] neg_hi:[0,1]
	s_nop 0
	v_pk_add_f32 v[4:5], v[6:7], v[4:5]
	v_pk_add_f32 v[6:7], v[10:11], v[16:17]
	v_pk_add_f32 v[4:5], v[22:23], v[4:5]
	v_pk_add_f32 v[8:9], v[6:7], v[10:11] neg_lo:[0,1] neg_hi:[0,1]
	v_pk_mul_f32 v[4:5], v[14:15], v[4:5]
	v_pk_add_f32 v[8:9], v[16:17], v[8:9] neg_lo:[0,1] neg_hi:[0,1]
	v_cvt_f32_i32_e32 v15, v31
	v_pk_add_f32 v[4:5], v[8:9], v[4:5]
	v_cvt_f32_i32_e32 v14, v24
	v_pk_add_f32 v[8:9], v[6:7], v[4:5]
	s_nop 0
	v_pk_mul_f32 v[10:11], v[8:9], v[8:9]
	v_pk_add_f32 v[6:7], v[8:9], v[6:7] neg_lo:[0,1] neg_hi:[0,1]
	v_pk_fma_f32 v[12:13], v[10:11], s[82:83], v[32:33] op_sel_hi:[1,0,0]
	v_pk_add_f32 v[4:5], v[4:5], v[6:7] neg_lo:[0,1] neg_hi:[0,1]
	v_ldexp_f32 v6, v8, 1
	v_pk_fma_f32 v[12:13], v[10:11], v[12:13], s[84:85] op_sel_hi:[1,1,0]
	v_ldexp_f32 v7, v9, 1
	v_pk_mul_f32 v[8:9], v[8:9], v[10:11]
	v_pk_mul_f32 v[10:11], v[14:15], s[86:87] op_sel_hi:[1,0]
	v_pk_mul_f32 v[8:9], v[8:9], v[12:13]
	v_pk_fma_f32 v[18:19], v[14:15], s[86:87], v[10:11] op_sel_hi:[1,0,1] neg_lo:[0,0,1] neg_hi:[0,0,1]
	v_pk_add_f32 v[12:13], v[6:7], v[8:9]
	v_ldexp_f32 v17, v5, 1
	v_pk_add_f32 v[6:7], v[12:13], v[6:7] neg_lo:[0,1] neg_hi:[0,1]
	v_pk_fma_f32 v[14:15], v[14:15], s[88:89], v[18:19] op_sel_hi:[1,0,1]
	v_pk_add_f32 v[6:7], v[8:9], v[6:7] neg_lo:[0,1] neg_hi:[0,1]
	v_ldexp_f32 v4, v4, 1
	v_mov_b32_e32 v8, v10
	v_mov_b32_e32 v9, v7
	v_mov_b32_e32 v16, v14
	v_mov_b32_e32 v5, v17
	v_pk_add_f32 v[8:9], v[8:9], v[16:17]
	v_pk_add_f32 v[16:17], v[4:5], v[6:7]
	v_mov_b32_e32 v7, v13
	v_mov_b32_e32 v5, v17
	v_pk_add_f32 v[18:19], v[10:11], v[14:15]
	v_pk_add_f32 v[4:5], v[4:5], v[6:7]
	v_pk_add_f32 v[6:7], v[12:13], v[16:17]
	v_mov_b32_e32 v48, v12
	v_pk_add_f32 v[22:23], v[18:19], v[6:7]
	v_mov_b32_e32 v46, v6
	v_mov_b32_e32 v47, v23
	v_mov_b32_e32 v49, v19
	v_pk_add_f32 v[46:47], v[46:47], v[48:49] neg_lo:[0,1] neg_hi:[0,1]
	v_mov_b32_e32 v32, v22
	v_mov_b32_e32 v33, v19
	v_mov_b32_e32 v34, v18
	v_mov_b32_e32 v35, v11
	v_mov_b32_e32 v48, v18
	v_mov_b32_e32 v49, v23
	v_mov_b32_e32 v11, v47
	v_pk_add_f32 v[32:33], v[32:33], v[34:35] neg_lo:[0,1] neg_hi:[0,1]
	v_mov_b32_e32 v34, v6
	v_mov_b32_e32 v35, v15
	v_pk_add_f32 v[10:11], v[48:49], v[10:11] neg_lo:[0,1] neg_hi:[0,1]
	v_pk_add_f32 v[34:35], v[34:35], v[32:33] neg_lo:[0,1] neg_hi:[0,1]
	v_mov_b32_e32 v48, v10
	v_mov_b32_e32 v49, v33
	v_mov_b32_e32 v50, v22
	v_mov_b32_e32 v51, v7
	v_mov_b32_e32 v33, v13
	v_pk_add_f32 v[48:49], v[14:15], v[48:49] neg_lo:[0,1] neg_hi:[0,1]
	v_pk_add_f32 v[32:33], v[50:51], v[32:33] neg_lo:[0,1] neg_hi:[0,1]
	v_mov_b32_e32 v15, v19
	v_pk_add_f32 v[8:9], v[8:9], v[32:33] neg_lo:[0,1] neg_hi:[0,1]
	v_pk_add_f32 v[10:11], v[14:15], v[10:11] neg_lo:[0,1] neg_hi:[0,1]
	v_pk_add_f32 v[4:5], v[4:5], v[46:47] neg_lo:[0,1] neg_hi:[0,1]
	v_pk_add_f32 v[6:7], v[6:7], v[12:13] neg_lo:[0,1] neg_hi:[0,1]
	v_pk_add_f32 v[12:13], v[4:5], v[10:11]
	v_mov_b32_e32 v11, v35
	v_mov_b32_e32 v5, v9
	v_pk_add_f32 v[14:15], v[34:35], v[8:9]
	v_pk_add_f32 v[4:5], v[10:11], v[4:5]
	v_mov_b32_e32 v8, v12
	v_pk_add_f32 v[4:5], v[4:5], v[48:49] neg_lo:[0,1] neg_hi:[0,1]
	v_mov_b32_e32 v9, v15
	v_pk_add_f32 v[6:7], v[16:17], v[6:7] neg_lo:[0,1] neg_hi:[0,1]
	v_pk_add_f32 v[8:9], v[8:9], v[4:5] neg_lo:[0,1] neg_hi:[0,1]
	v_pk_add_f32 v[4:5], v[6:7], v[4:5] neg_lo:[0,1] neg_hi:[0,1]
	v_pk_add_f32 v[8:9], v[10:11], v[8:9] neg_lo:[0,1] neg_hi:[0,1]
	v_pk_add_f32 v[6:7], v[14:15], v[12:13]
	v_pk_add_f32 v[4:5], v[4:5], v[8:9]
	v_pk_add_f32 v[8:9], v[22:23], v[6:7]
	s_nop 0
	v_pk_add_f32 v[10:11], v[8:9], v[22:23] neg_lo:[0,1] neg_hi:[0,1]
	s_nop 0
	v_pk_add_f32 v[6:7], v[6:7], v[10:11] neg_lo:[0,1] neg_hi:[0,1]
	s_nop 0
	v_pk_add_f32 v[4:5], v[4:5], v[6:7]
	s_nop 0
	v_pk_add_f32 v[4:5], v[8:9], v[4:5]
	s_nop 0
	v_cndmask_b32_e64 v4, v42, v4, s[10:11]
	v_cmp_neq_f32_e64 s[10:11], s18, v52
	s_nop 1
	v_cndmask_b32_e64 v5, v42, v5, s[10:11]
	v_cmp_ngt_f32_e64 s[10:11], -1.0, v52
	s_nop 1
	v_cndmask_b32_e64 v5, v43, v5, s[10:11]
	v_cmp_ngt_f32_e64 s[10:11], -1.0, v45
	s_nop 1
	v_cndmask_b32_e64 v4, v43, v4, s[10:11]
	v_cmp_neq_f32_e64 s[10:11], -1.0, v45
	s_nop 1
	v_cndmask_b32_e64 v4, v44, v4, s[10:11]
	v_cmp_neq_f32_e64 s[10:11], -1.0, v52
	s_nop 1
	v_cndmask_b32_e64 v5, v44, v5, s[10:11]
	v_cmp_lt_f32_e64 s[10:11], |v52|, s19
	s_nop 1
	v_cndmask_b32_e64 v5, v5, v52, s[10:11]
	v_cmp_lt_f32_e64 s[10:11], |v45|, s19
	s_nop 1
	v_cndmask_b32_e64 v4, v4, v45, s[10:11]
	v_pk_add_f32 v[2:3], v[2:3], v[4:5] neg_lo:[0,1] neg_hi:[0,1]
	global_store_dwordx4 v[20:21], v[0:3], off offset:96
	s_branch .LBB0_458
